# hand-written LayerNorm row loops (gamma/beta held in registers) on top of scan + lora_in
# speedup vs baseline: 1.0067x; 1.0045x over previous
; template <bool WRITE_BF, bool WRITE_F32, bool WRITE_F8 = false>
; __device__ __forceinline__ void ln_phase(Frame& F, const bf16* T, const float* g, const float* b, unsigned char* x8 = nullptr) {
;     float* Y = F.out; bf16* xb = (bf16*)(F.ws + WS_XB);
;     int lane_ = threadIdx.x & 63; asm volatile("" : "+v"(lane_));
;     for (int row = F.gw; row < MR; row += F.NGW) {
;         const u32x4* tr = (const u32x4*)(T + (size_t)row * D) + lane_;
;         float v[64]; float s = 0.f;
; #pragma unroll
;         for (int j = 0; j < 8; ++j) { const u32x4 w = tr[64 * j];
; #pragma unroll
;             for (int q = 0; q < 4; ++q) { v[8 * j + 2 * q] = __uint_as_float(w[q] << 16); v[8 * j + 2 * q + 1] = __uint_as_float(w[q] & 0xffff0000u); s += v[8 * j + 2 * q] + v[8 * j + 2 * q + 1]; } }
.LBB0_317:
	s_load_dwordx4 s[4:7], s[74:75], 0x28
	s_load_dwordx4 s[52:55], s[74:75], 0x100
	v_mbcnt_lo_u32_b32 v203, -1, 0
	v_mbcnt_hi_u32_b32 v203, -1, v203
	v_lshlrev_b32_e32 v78, 4, v203
	v_add_u32_e32 v241, 0x1000, v78
	v_lshlrev_b32_e32 v1, 3, v203
	v_lshlrev_b32_e32 v92, 5, v203
	v_add_u32_e32 v24, 0x1000, v92
	v_add_u32_e32 v169, 0x2000, v92
	v_add_u32_e32 v179, 0x3000, v92
	s_waitcnt lgkmcnt(0)
	global_load_dwordx4 v[212:215], v92, s[4:5]
	global_load_dwordx4 v[216:219], v92, s[4:5] offset:16
	global_load_dwordx4 v[186:189], v92, s[6:7]
	global_load_dwordx4 v[190:193], v92, s[6:7] offset:16
	global_load_dwordx4 v[220:223], v92, s[4:5] offset:2048
	global_load_dwordx4 v[224:227], v92, s[4:5] offset:2064
	global_load_dwordx4 v[194:197], v92, s[6:7] offset:2048
	global_load_dwordx4 v[198:201], v92, s[6:7] offset:2064
	global_load_dwordx4 v[228:231], v24, s[4:5]
	global_load_dwordx4 v[232:235], v24, s[4:5] offset:16
	global_load_dwordx4 v[242:245], v24, s[6:7]
	global_load_dwordx4 v[246:249], v24, s[6:7] offset:16
	global_load_dwordx4 v[236:239], v24, s[4:5] offset:2048
	global_load_dwordx4 v[46:49], v24, s[4:5] offset:2064
	global_load_dwordx4 v[250:253], v24, s[6:7] offset:2048
	global_load_dwordx4 v[2:5], v24, s[6:7] offset:2064
	global_load_dwordx4 v[50:53], v169, s[4:5]
	global_load_dwordx4 v[54:57], v169, s[4:5] offset:16
	global_load_dwordx4 v[6:9], v169, s[6:7]
	global_load_dwordx4 v[10:13], v169, s[6:7] offset:16
	global_load_dwordx4 v[58:61], v169, s[4:5] offset:2048
	global_load_dwordx4 v[62:65], v169, s[4:5] offset:2064
	global_load_dwordx4 v[14:17], v169, s[6:7] offset:2048
	global_load_dwordx4 v[80:83], v169, s[6:7] offset:2064
	global_load_dwordx4 v[66:69], v179, s[4:5]
	global_load_dwordx4 v[70:73], v179, s[4:5] offset:16
	global_load_dwordx4 v[84:87], v179, s[6:7]
	global_load_dwordx4 v[88:91], v179, s[6:7] offset:16
	global_load_dwordx4 v[74:77], v179, s[4:5] offset:2048
	global_load_dwordx4 v[182:185], v179, s[4:5] offset:2064
	global_load_dwordx4 v[172:175], v179, s[6:7] offset:2048
	global_load_dwordx4 v[156:159], v179, s[6:7] offset:2064
	s_add_u32 s34, s54, 0x39900000
	s_addc_u32 s35, s55, 0
	s_mov_b32 s41, s94
.Lln1_row:
	s_lshl_b32 s36, s41, 13
	s_add_u32 s36, s34, s36
	s_addc_u32 s37, s35, 0
	global_load_dwordx4 v[104:107], v78, s[36:37]
	global_load_dwordx4 v[112:115], v78, s[36:37] offset:1024
	global_load_dwordx4 v[120:123], v78, s[36:37] offset:2048
	global_load_dwordx4 v[128:131], v78, s[36:37] offset:3072
	global_load_dwordx4 v[136:139], v241, s[36:37]
	global_load_dwordx4 v[144:147], v241, s[36:37] offset:1024
	global_load_dwordx4 v[152:155], v241, s[36:37] offset:2048
	global_load_dwordx4 v[208:211], v241, s[36:37] offset:3072
	v_mov_b32_e32 v160, 0
	v_mov_b32_e32 v161, 0
	s_waitcnt vmcnt(0)
	v_lshlrev_b32_e32 v100, 16, v104
	v_and_b32_e32 v101, 0xffff0000, v104
	v_lshlrev_b32_e32 v102, 16, v105
	v_and_b32_e32 v103, 0xffff0000, v105
	v_lshlrev_b32_e32 v104, 16, v106
	v_and_b32_e32 v105, 0xffff0000, v106
	v_lshlrev_b32_e32 v106, 16, v107
	v_and_b32_e32 v107, 0xffff0000, v107
	v_pk_add_f32 v[160:161], v[160:161], v[100:101]
	v_pk_add_f32 v[160:161], v[160:161], v[102:103]
	v_pk_add_f32 v[160:161], v[160:161], v[104:105]
	v_pk_add_f32 v[160:161], v[160:161], v[106:107]
	v_lshlrev_b32_e32 v108, 16, v112
	v_and_b32_e32 v109, 0xffff0000, v112
	v_lshlrev_b32_e32 v110, 16, v113
	v_and_b32_e32 v111, 0xffff0000, v113
	v_lshlrev_b32_e32 v112, 16, v114
	v_and_b32_e32 v113, 0xffff0000, v114
	v_lshlrev_b32_e32 v114, 16, v115
	v_and_b32_e32 v115, 0xffff0000, v115
	v_pk_add_f32 v[160:161], v[160:161], v[108:109]
	v_pk_add_f32 v[160:161], v[160:161], v[110:111]
	v_pk_add_f32 v[160:161], v[160:161], v[112:113]
	v_pk_add_f32 v[160:161], v[160:161], v[114:115]
	v_lshlrev_b32_e32 v116, 16, v120
	v_and_b32_e32 v117, 0xffff0000, v120
	v_lshlrev_b32_e32 v118, 16, v121
	v_and_b32_e32 v119, 0xffff0000, v121
	v_lshlrev_b32_e32 v120, 16, v122
	v_and_b32_e32 v121, 0xffff0000, v122
	v_lshlrev_b32_e32 v122, 16, v123
	v_and_b32_e32 v123, 0xffff0000, v123
	v_pk_add_f32 v[160:161], v[160:161], v[116:117]
	v_pk_add_f32 v[160:161], v[160:161], v[118:119]
	v_pk_add_f32 v[160:161], v[160:161], v[120:121]
	v_pk_add_f32 v[160:161], v[160:161], v[122:123]
	v_lshlrev_b32_e32 v124, 16, v128
	v_and_b32_e32 v125, 0xffff0000, v128
	v_lshlrev_b32_e32 v126, 16, v129
	v_and_b32_e32 v127, 0xffff0000, v129
	v_lshlrev_b32_e32 v128, 16, v130
	v_and_b32_e32 v129, 0xffff0000, v130
	v_lshlrev_b32_e32 v130, 16, v131
	v_and_b32_e32 v131, 0xffff0000, v131
	v_pk_add_f32 v[160:161], v[160:161], v[124:125]
	v_pk_add_f32 v[160:161], v[160:161], v[126:127]
	v_pk_add_f32 v[160:161], v[160:161], v[128:129]
	v_pk_add_f32 v[160:161], v[160:161], v[130:131]
	v_lshlrev_b32_e32 v132, 16, v136
	v_and_b32_e32 v133, 0xffff0000, v136
	v_lshlrev_b32_e32 v134, 16, v137
	v_and_b32_e32 v135, 0xffff0000, v137
	v_lshlrev_b32_e32 v136, 16, v138
	v_and_b32_e32 v137, 0xffff0000, v138
	v_lshlrev_b32_e32 v138, 16, v139
	v_and_b32_e32 v139, 0xffff0000, v139
	v_pk_add_f32 v[160:161], v[160:161], v[132:133]
	v_pk_add_f32 v[160:161], v[160:161], v[134:135]
	v_pk_add_f32 v[160:161], v[160:161], v[136:137]
	v_pk_add_f32 v[160:161], v[160:161], v[138:139]
	v_lshlrev_b32_e32 v140, 16, v144
	v_and_b32_e32 v141, 0xffff0000, v144
	v_lshlrev_b32_e32 v142, 16, v145
	v_and_b32_e32 v143, 0xffff0000, v145
	v_lshlrev_b32_e32 v144, 16, v146
	v_and_b32_e32 v145, 0xffff0000, v146
	v_lshlrev_b32_e32 v146, 16, v147
	v_and_b32_e32 v147, 0xffff0000, v147
	v_pk_add_f32 v[160:161], v[160:161], v[140:141]
	v_pk_add_f32 v[160:161], v[160:161], v[142:143]
	v_pk_add_f32 v[160:161], v[160:161], v[144:145]
; template <bool WRITE_BF, bool WRITE_F32, bool WRITE_F8 = false>
; __device__ __forceinline__ void ln_phase(Frame& F, const bf16* T, const float* g, const float* b, unsigned char* x8 = nullptr) {
;     ...
;             for (int q = 0; q < 4; ++q) { v[8 * j + 2 * q] = __uint_as_float(w[q] << 16); v[8 * j + 2 * q + 1] = __uint_as_float(w[q] & 0xffff0000u); s += v[8 * j + 2 * q] + v[8 * j + 2 * q + 1]; } }
;         const float mean = wave_sum(s) * (1.f / D); float s2 = 0.f;
; #pragma unroll
;         for (int i = 0; i < 64; ++i) { v[i] -= mean; s2 += v[i] * v[i]; }
	v_pk_add_f32 v[160:161], v[160:161], v[146:147]
	v_lshlrev_b32_e32 v148, 16, v152
	v_and_b32_e32 v149, 0xffff0000, v152
	v_lshlrev_b32_e32 v150, 16, v153
	v_and_b32_e32 v151, 0xffff0000, v153
	v_lshlrev_b32_e32 v152, 16, v154
	v_and_b32_e32 v153, 0xffff0000, v154
	v_lshlrev_b32_e32 v154, 16, v155
	v_and_b32_e32 v155, 0xffff0000, v155
	v_pk_add_f32 v[160:161], v[160:161], v[148:149]
	v_pk_add_f32 v[160:161], v[160:161], v[150:151]
	v_pk_add_f32 v[160:161], v[160:161], v[152:153]
	v_pk_add_f32 v[160:161], v[160:161], v[154:155]
	v_lshlrev_b32_e32 v204, 16, v208
	v_and_b32_e32 v205, 0xffff0000, v208
	v_lshlrev_b32_e32 v206, 16, v209
	v_and_b32_e32 v207, 0xffff0000, v209
	v_lshlrev_b32_e32 v208, 16, v210
	v_and_b32_e32 v209, 0xffff0000, v210
	v_lshlrev_b32_e32 v210, 16, v211
	v_and_b32_e32 v211, 0xffff0000, v211
	v_pk_add_f32 v[160:161], v[160:161], v[204:205]
	v_pk_add_f32 v[160:161], v[160:161], v[206:207]
	v_pk_add_f32 v[160:161], v[160:161], v[208:209]
	v_pk_add_f32 v[160:161], v[160:161], v[210:211]
	v_add_f32_e32 v99, v160, v161
	s_nop 1
	v_add_f32_dpp v99, v99, v99 quad_perm:[1,0,3,2] row_mask:0xf bank_mask:0xf
	s_nop 1
	v_add_f32_dpp v99, v99, v99 quad_perm:[2,3,0,1] row_mask:0xf bank_mask:0xf
	s_nop 1
	v_add_f32_dpp v99, v99, v99 row_half_mirror row_mask:0xf bank_mask:0xf
	s_nop 1
	v_add_f32_dpp v99, v99, v99 row_mirror row_mask:0xf bank_mask:0xf
	s_nop 1
	v_readlane_b32 s28, v99, 0
	v_readlane_b32 s29, v99, 16
	v_readlane_b32 s30, v99, 32
	v_readlane_b32 s31, v99, 48
	s_nop 1
	v_mov_b32_e32 v99, s28
	v_add_f32_e32 v99, s29, v99
	v_add_f32_e32 v203, s30, v99
	v_add_f32_e32 v99, s31, v203
	v_mul_f32_e32 v18, 0xb9800000, v99
	v_mov_b32_e32 v160, 0
	v_mov_b32_e32 v161, 0
	v_pk_add_f32 v[100:101], v[100:101], v[18:19] op_sel_hi:[1,0]
	v_pk_add_f32 v[102:103], v[102:103], v[18:19] op_sel_hi:[1,0]
	v_pk_add_f32 v[104:105], v[104:105], v[18:19] op_sel_hi:[1,0]
	v_pk_add_f32 v[106:107], v[106:107], v[18:19] op_sel_hi:[1,0]
	v_pk_add_f32 v[108:109], v[108:109], v[18:19] op_sel_hi:[1,0]
	v_pk_add_f32 v[110:111], v[110:111], v[18:19] op_sel_hi:[1,0]
	v_pk_add_f32 v[112:113], v[112:113], v[18:19] op_sel_hi:[1,0]
	v_pk_add_f32 v[114:115], v[114:115], v[18:19] op_sel_hi:[1,0]
	v_pk_add_f32 v[116:117], v[116:117], v[18:19] op_sel_hi:[1,0]
	v_pk_add_f32 v[118:119], v[118:119], v[18:19] op_sel_hi:[1,0]
	v_pk_add_f32 v[120:121], v[120:121], v[18:19] op_sel_hi:[1,0]
	v_pk_add_f32 v[122:123], v[122:123], v[18:19] op_sel_hi:[1,0]
	v_pk_add_f32 v[124:125], v[124:125], v[18:19] op_sel_hi:[1,0]
	v_pk_add_f32 v[126:127], v[126:127], v[18:19] op_sel_hi:[1,0]
	v_pk_add_f32 v[128:129], v[128:129], v[18:19] op_sel_hi:[1,0]
	v_pk_add_f32 v[130:131], v[130:131], v[18:19] op_sel_hi:[1,0]
	v_pk_add_f32 v[132:133], v[132:133], v[18:19] op_sel_hi:[1,0]
	v_pk_add_f32 v[134:135], v[134:135], v[18:19] op_sel_hi:[1,0]
	v_pk_add_f32 v[136:137], v[136:137], v[18:19] op_sel_hi:[1,0]
	v_pk_add_f32 v[138:139], v[138:139], v[18:19] op_sel_hi:[1,0]
	v_pk_add_f32 v[140:141], v[140:141], v[18:19] op_sel_hi:[1,0]
	v_pk_add_f32 v[142:143], v[142:143], v[18:19] op_sel_hi:[1,0]
	v_pk_add_f32 v[144:145], v[144:145], v[18:19] op_sel_hi:[1,0]
	v_pk_add_f32 v[146:147], v[146:147], v[18:19] op_sel_hi:[1,0]
	v_pk_add_f32 v[148:149], v[148:149], v[18:19] op_sel_hi:[1,0]
	v_pk_add_f32 v[150:151], v[150:151], v[18:19] op_sel_hi:[1,0]
	v_pk_add_f32 v[152:153], v[152:153], v[18:19] op_sel_hi:[1,0]
	v_pk_add_f32 v[154:155], v[154:155], v[18:19] op_sel_hi:[1,0]
	v_pk_add_f32 v[204:205], v[204:205], v[18:19] op_sel_hi:[1,0]
	v_pk_add_f32 v[206:207], v[206:207], v[18:19] op_sel_hi:[1,0]
	v_pk_add_f32 v[208:209], v[208:209], v[18:19] op_sel_hi:[1,0]
	v_pk_add_f32 v[210:211], v[210:211], v[18:19] op_sel_hi:[1,0]
	v_pk_fma_f32 v[160:161], v[100:101], v[100:101], v[160:161]
	v_pk_fma_f32 v[160:161], v[102:103], v[102:103], v[160:161]
	v_pk_fma_f32 v[160:161], v[104:105], v[104:105], v[160:161]
	v_pk_fma_f32 v[160:161], v[106:107], v[106:107], v[160:161]
	v_pk_fma_f32 v[160:161], v[108:109], v[108:109], v[160:161]
	v_pk_fma_f32 v[160:161], v[110:111], v[110:111], v[160:161]
	v_pk_fma_f32 v[160:161], v[112:113], v[112:113], v[160:161]
	v_pk_fma_f32 v[160:161], v[114:115], v[114:115], v[160:161]
	v_pk_fma_f32 v[160:161], v[116:117], v[116:117], v[160:161]
	v_pk_fma_f32 v[160:161], v[118:119], v[118:119], v[160:161]
	v_pk_fma_f32 v[160:161], v[120:121], v[120:121], v[160:161]
	v_pk_fma_f32 v[160:161], v[122:123], v[122:123], v[160:161]
	v_pk_fma_f32 v[160:161], v[124:125], v[124:125], v[160:161]
	v_pk_fma_f32 v[160:161], v[126:127], v[126:127], v[160:161]
	v_pk_fma_f32 v[160:161], v[128:129], v[128:129], v[160:161]
	v_pk_fma_f32 v[160:161], v[130:131], v[130:131], v[160:161]
	v_pk_fma_f32 v[160:161], v[132:133], v[132:133], v[160:161]
	v_pk_fma_f32 v[160:161], v[134:135], v[134:135], v[160:161]
	v_pk_fma_f32 v[160:161], v[136:137], v[136:137], v[160:161]
	v_pk_fma_f32 v[160:161], v[138:139], v[138:139], v[160:161]
	v_pk_fma_f32 v[160:161], v[140:141], v[140:141], v[160:161]
	v_pk_fma_f32 v[160:161], v[142:143], v[142:143], v[160:161]
	v_pk_fma_f32 v[160:161], v[144:145], v[144:145], v[160:161]
	v_pk_fma_f32 v[160:161], v[146:147], v[146:147], v[160:161]
	v_pk_fma_f32 v[160:161], v[148:149], v[148:149], v[160:161]
	v_pk_fma_f32 v[160:161], v[150:151], v[150:151], v[160:161]
	v_pk_fma_f32 v[160:161], v[152:153], v[152:153], v[160:161]
	v_pk_fma_f32 v[160:161], v[154:155], v[154:155], v[160:161]
	v_pk_fma_f32 v[160:161], v[204:205], v[204:205], v[160:161]
	v_pk_fma_f32 v[160:161], v[206:207], v[206:207], v[160:161]
	v_pk_fma_f32 v[160:161], v[208:209], v[208:209], v[160:161]
; __device__ __forceinline__ unsigned pk2(float lo, float hi) { return cvt_pk_bf16(lo, hi); }
; template <bool WRITE_BF, bool WRITE_F32, bool WRITE_F8 = false>
; __device__ __forceinline__ void ln_phase(Frame& F, const bf16* T, const float* g, const float* b, unsigned char* x8 = nullptr) {
;     ...
;         for (int i = 0; i < 64; ++i) { v[i] -= mean; s2 += v[i] * v[i]; }
;         const float rstd = 1.f / sqrtf(wave_sum(s2) * (1.f / D) + 1e-5f);
; #pragma unroll
;         for (int j = 0; j < 8; ++j) { const int c0 = 8 * (lane_ + 64 * j);
;             const f32x4 g0 = *(const f32x4*)(g + c0), g1 = *(const f32x4*)(g + c0 + 4), b0 = *(const f32x4*)(b + c0), b1 = *(const f32x4*)(b + c0 + 4);
;             const f32x4 y0 = (f32x4){v[8 * j], v[8 * j + 1], v[8 * j + 2], v[8 * j + 3]} * rstd * g0 + b0, y1 = (f32x4){v[8 * j + 4], v[8 * j + 5], v[8 * j + 6], v[8 * j + 7]} * rstd * g1 + b1;
;             if (WRITE_F32) { *(f32x4*)(Y + (size_t)row * D + c0) = y0; *(f32x4*)(Y + (size_t)row * D + c0 + 4) = y1; }
;             if (WRITE_BF) *(u32x4*)(xb + (size_t)row * D + c0) = (u32x4){pk2(y0[0], y0[1]), pk2(y0[2], y0[3]), pk2(y1[0], y1[1]), pk2(y1[2], y1[3])};
	v_pk_fma_f32 v[160:161], v[210:211], v[210:211], v[160:161]
	v_add_f32_e32 v99, v160, v161
	s_nop 1
	v_add_f32_dpp v99, v99, v99 quad_perm:[1,0,3,2] row_mask:0xf bank_mask:0xf
	s_nop 1
	v_add_f32_dpp v99, v99, v99 quad_perm:[2,3,0,1] row_mask:0xf bank_mask:0xf
	s_nop 1
	v_add_f32_dpp v99, v99, v99 row_half_mirror row_mask:0xf bank_mask:0xf
	s_nop 1
	v_add_f32_dpp v99, v99, v99 row_mirror row_mask:0xf bank_mask:0xf
	s_nop 1
	v_readlane_b32 s28, v99, 0
	v_readlane_b32 s29, v99, 16
	v_readlane_b32 s30, v99, 32
	v_readlane_b32 s31, v99, 48
	s_nop 1
	v_mov_b32_e32 v99, s28
	v_add_f32_e32 v99, s29, v99
	v_add_f32_e32 v203, s30, v99
	v_add_f32_e32 v99, s31, v203
	v_mov_b32_e32 v203, 0x3727c5ac
	v_fmac_f32_e32 v203, 0x39800000, v99
	v_sqrt_f32_e32 v203, v203
	s_nop 0
	v_rcp_f32_e32 v18, v203
	s_nop 0
	v_pk_mul_f32 v[100:101], v[100:101], v[18:19] op_sel_hi:[1,0]
	v_pk_mul_f32 v[102:103], v[102:103], v[18:19] op_sel_hi:[1,0]
	v_pk_mul_f32 v[104:105], v[104:105], v[18:19] op_sel_hi:[1,0]
	v_pk_mul_f32 v[106:107], v[106:107], v[18:19] op_sel_hi:[1,0]
	v_pk_mul_f32 v[108:109], v[108:109], v[18:19] op_sel_hi:[1,0]
	v_pk_mul_f32 v[110:111], v[110:111], v[18:19] op_sel_hi:[1,0]
	v_pk_mul_f32 v[112:113], v[112:113], v[18:19] op_sel_hi:[1,0]
	v_pk_mul_f32 v[114:115], v[114:115], v[18:19] op_sel_hi:[1,0]
	v_pk_mul_f32 v[116:117], v[116:117], v[18:19] op_sel_hi:[1,0]
	v_pk_mul_f32 v[118:119], v[118:119], v[18:19] op_sel_hi:[1,0]
	v_pk_mul_f32 v[120:121], v[120:121], v[18:19] op_sel_hi:[1,0]
	v_pk_mul_f32 v[122:123], v[122:123], v[18:19] op_sel_hi:[1,0]
	v_pk_mul_f32 v[124:125], v[124:125], v[18:19] op_sel_hi:[1,0]
	v_pk_mul_f32 v[126:127], v[126:127], v[18:19] op_sel_hi:[1,0]
	v_pk_mul_f32 v[128:129], v[128:129], v[18:19] op_sel_hi:[1,0]
	v_pk_mul_f32 v[130:131], v[130:131], v[18:19] op_sel_hi:[1,0]
	v_pk_mul_f32 v[132:133], v[132:133], v[18:19] op_sel_hi:[1,0]
	v_pk_mul_f32 v[134:135], v[134:135], v[18:19] op_sel_hi:[1,0]
	v_pk_mul_f32 v[136:137], v[136:137], v[18:19] op_sel_hi:[1,0]
	v_pk_mul_f32 v[138:139], v[138:139], v[18:19] op_sel_hi:[1,0]
	v_pk_mul_f32 v[140:141], v[140:141], v[18:19] op_sel_hi:[1,0]
	v_pk_mul_f32 v[142:143], v[142:143], v[18:19] op_sel_hi:[1,0]
	v_pk_mul_f32 v[144:145], v[144:145], v[18:19] op_sel_hi:[1,0]
	v_pk_mul_f32 v[146:147], v[146:147], v[18:19] op_sel_hi:[1,0]
	v_pk_mul_f32 v[148:149], v[148:149], v[18:19] op_sel_hi:[1,0]
	v_pk_mul_f32 v[150:151], v[150:151], v[18:19] op_sel_hi:[1,0]
	v_pk_mul_f32 v[152:153], v[152:153], v[18:19] op_sel_hi:[1,0]
	v_pk_mul_f32 v[154:155], v[154:155], v[18:19] op_sel_hi:[1,0]
	v_pk_mul_f32 v[204:205], v[204:205], v[18:19] op_sel_hi:[1,0]
	v_pk_mul_f32 v[206:207], v[206:207], v[18:19] op_sel_hi:[1,0]
	v_pk_mul_f32 v[208:209], v[208:209], v[18:19] op_sel_hi:[1,0]
	v_pk_mul_f32 v[210:211], v[210:211], v[18:19] op_sel_hi:[1,0]
	v_pk_fma_f32 v[100:101], v[212:213], v[100:101], v[186:187]
	v_pk_fma_f32 v[102:103], v[214:215], v[102:103], v[188:189]
	v_pk_fma_f32 v[104:105], v[216:217], v[104:105], v[190:191]
	v_pk_fma_f32 v[106:107], v[218:219], v[106:107], v[192:193]
	v_pk_fma_f32 v[108:109], v[220:221], v[108:109], v[194:195]
	v_pk_fma_f32 v[110:111], v[222:223], v[110:111], v[196:197]
	v_pk_fma_f32 v[112:113], v[224:225], v[112:113], v[198:199]
	v_pk_fma_f32 v[114:115], v[226:227], v[114:115], v[200:201]
	v_pk_fma_f32 v[116:117], v[228:229], v[116:117], v[242:243]
	v_pk_fma_f32 v[118:119], v[230:231], v[118:119], v[244:245]
	v_pk_fma_f32 v[120:121], v[232:233], v[120:121], v[246:247]
	v_pk_fma_f32 v[122:123], v[234:235], v[122:123], v[248:249]
	v_pk_fma_f32 v[124:125], v[236:237], v[124:125], v[250:251]
	v_pk_fma_f32 v[126:127], v[238:239], v[126:127], v[252:253]
	v_pk_fma_f32 v[128:129], v[46:47], v[128:129], v[2:3]
	v_pk_fma_f32 v[130:131], v[48:49], v[130:131], v[4:5]
	v_pk_fma_f32 v[132:133], v[50:51], v[132:133], v[6:7]
	v_pk_fma_f32 v[134:135], v[52:53], v[134:135], v[8:9]
	v_pk_fma_f32 v[136:137], v[54:55], v[136:137], v[10:11]
	v_pk_fma_f32 v[138:139], v[56:57], v[138:139], v[12:13]
	v_pk_fma_f32 v[140:141], v[58:59], v[140:141], v[14:15]
	v_pk_fma_f32 v[142:143], v[60:61], v[142:143], v[16:17]
	v_pk_fma_f32 v[144:145], v[62:63], v[144:145], v[80:81]
	v_pk_fma_f32 v[146:147], v[64:65], v[146:147], v[82:83]
	v_pk_fma_f32 v[148:149], v[66:67], v[148:149], v[84:85]
	v_pk_fma_f32 v[150:151], v[68:69], v[150:151], v[86:87]
	v_pk_fma_f32 v[152:153], v[70:71], v[152:153], v[88:89]
	v_pk_fma_f32 v[154:155], v[72:73], v[154:155], v[90:91]
	v_pk_fma_f32 v[204:205], v[74:75], v[204:205], v[172:173]
	v_pk_fma_f32 v[206:207], v[76:77], v[206:207], v[174:175]
	v_pk_fma_f32 v[208:209], v[182:183], v[208:209], v[156:157]
	v_pk_fma_f32 v[210:211], v[184:185], v[210:211], v[158:159]
	s_lshl_b32 s38, s41, 13
	s_add_u32 s38, s54, s38
	s_addc_u32 s39, s55, 0
	s_add_u32 s38, s38, 0x100000
	s_addc_u32 s39, s39, 0
	s_lshl_b32 s42, s41, 12
	s_add_u32 s42, s54, s42
	s_addc_u32 s43, s55, 0
	s_add_u32 s42, s42, 0x18500000
	s_addc_u32 s43, s43, 0
	v_mov_b32_e32 v203, 0x42fe0000
	s_mov_b32 s44, 0xc2fe0000
	s_mov_b32 s45, 0x040c0c00
	s_mov_b32 s46, 0x0c04000c
	v_cvt_pk_bf16_f32 v254, v100, v101
	v_cvt_pk_bf16_f32 v255, v102, v103
	v_cvt_pk_bf16_f32 v94, v104, v105
	v_cvt_pk_bf16_f32 v95, v106, v107
	global_store_dwordx2 v78, v[254:255], s[38:39]
	global_store_dwordx2 v78, v[94:95], s[38:39] offset:8
	v_mul_f32_e32 v100, 0x41fe0000, v100
	v_mul_f32_e32 v101, 0x41fe0000, v101
	v_mul_f32_e32 v102, 0x41fe0000, v102
	v_mul_f32_e32 v103, 0x41fe0000, v103
	v_mul_f32_e32 v104, 0x41fe0000, v104
	v_mul_f32_e32 v105, 0x41fe0000, v105
	v_mul_f32_e32 v106, 0x41fe0000, v106
	v_mul_f32_e32 v107, 0x41fe0000, v107
; __device__ __forceinline__ unsigned pk2(float lo, float hi) { return cvt_pk_bf16(lo, hi); }
; __device__ __forceinline__ unsigned pk4_i8(float a, float b, float c, float d, float s) {
;     const unsigned ua = __float_as_uint(__builtin_amdgcn_fmed3f(a * s, -127.f, 127.f) + 12582912.f), ub = __float_as_uint(__builtin_amdgcn_fmed3f(b * s, -127.f, 127.f) + 12582912.f);
;     const unsigned uc = __float_as_uint(__builtin_amdgcn_fmed3f(c * s, -127.f, 127.f) + 12582912.f), ud = __float_as_uint(__builtin_amdgcn_fmed3f(d * s, -127.f, 127.f) + 12582912.f);
;     return (ua & 0xffu) | ((ub & 0xffu) << 8) | ((uc & 0xffu) << 16) | (ud << 24);
; template <bool WRITE_BF, bool WRITE_F32, bool WRITE_F8 = false>
; __device__ __forceinline__ void ln_phase(Frame& F, const bf16* T, const float* g, const float* b, unsigned char* x8 = nullptr) {
;     ...
;         for (int j = 0; j < 8; ++j) { const int c0 = 8 * (lane_ + 64 * j);
;             const f32x4 g0 = *(const f32x4*)(g + c0), g1 = *(const f32x4*)(g + c0 + 4), b0 = *(const f32x4*)(b + c0), b1 = *(const f32x4*)(b + c0 + 4);
;             const f32x4 y0 = (f32x4){v[8 * j], v[8 * j + 1], v[8 * j + 2], v[8 * j + 3]} * rstd * g0 + b0, y1 = (f32x4){v[8 * j + 4], v[8 * j + 5], v[8 * j + 6], v[8 * j + 7]} * rstd * g1 + b1;
;             if (WRITE_F32) { *(f32x4*)(Y + (size_t)row * D + c0) = y0; *(f32x4*)(Y + (size_t)row * D + c0 + 4) = y1; }
;             if (WRITE_BF) *(u32x4*)(xb + (size_t)row * D + c0) = (u32x4){pk2(y0[0], y0[1]), pk2(y0[2], y0[3]), pk2(y1[0], y1[1]), pk2(y1[2], y1[3])};
;             if (WRITE_F8) *(u32x2*)(x8 + (size_t)row * D + c0) = (u32x2){pk4_i8(y0[0], y0[1], y0[2], y0[3], I8_ACT), pk4_i8(y1[0], y1[1], y1[2], y1[3], I8_ACT)}; }
	v_med3_f32 v100, v100, s44, v203
	v_med3_f32 v101, v101, s44, v203
	v_med3_f32 v102, v102, s44, v203
	v_med3_f32 v103, v103, s44, v203
	v_med3_f32 v104, v104, s44, v203
	v_med3_f32 v105, v105, s44, v203
	v_med3_f32 v106, v106, s44, v203
	v_med3_f32 v107, v107, s44, v203
	v_add_f32_e32 v100, 0x4b400000, v100
	v_add_f32_e32 v101, 0x4b400000, v101
	v_add_f32_e32 v102, 0x4b400000, v102
	v_add_f32_e32 v103, 0x4b400000, v103
	v_add_f32_e32 v104, 0x4b400000, v104
	v_add_f32_e32 v105, 0x4b400000, v105
	v_add_f32_e32 v106, 0x4b400000, v106
	v_add_f32_e32 v107, 0x4b400000, v107
	v_perm_b32 v100, v103, v100, s45
	v_perm_b32 v101, v102, v101, s46
	v_or_b32_e32 v176, v100, v101
	v_perm_b32 v104, v107, v104, s45
	v_perm_b32 v105, v106, v105, s46
	v_or_b32_e32 v177, v104, v105
	global_store_dwordx2 v1, v[176:177], s[42:43]
	v_cvt_pk_bf16_f32 v254, v108, v109
	v_cvt_pk_bf16_f32 v255, v110, v111
	v_cvt_pk_bf16_f32 v94, v112, v113
	v_cvt_pk_bf16_f32 v95, v114, v115
	global_store_dwordx2 v78, v[254:255], s[38:39] offset:1024
	global_store_dwordx2 v78, v[94:95], s[38:39] offset:1032
	v_mul_f32_e32 v108, 0x41fe0000, v108
	v_mul_f32_e32 v109, 0x41fe0000, v109
	v_mul_f32_e32 v110, 0x41fe0000, v110
	v_mul_f32_e32 v111, 0x41fe0000, v111
	v_mul_f32_e32 v112, 0x41fe0000, v112
	v_mul_f32_e32 v113, 0x41fe0000, v113
	v_mul_f32_e32 v114, 0x41fe0000, v114
	v_mul_f32_e32 v115, 0x41fe0000, v115
	v_med3_f32 v108, v108, s44, v203
	v_med3_f32 v109, v109, s44, v203
	v_med3_f32 v110, v110, s44, v203
	v_med3_f32 v111, v111, s44, v203
	v_med3_f32 v112, v112, s44, v203
	v_med3_f32 v113, v113, s44, v203
	v_med3_f32 v114, v114, s44, v203
	v_med3_f32 v115, v115, s44, v203
	v_add_f32_e32 v108, 0x4b400000, v108
	v_add_f32_e32 v109, 0x4b400000, v109
	v_add_f32_e32 v110, 0x4b400000, v110
	v_add_f32_e32 v111, 0x4b400000, v111
	v_add_f32_e32 v112, 0x4b400000, v112
	v_add_f32_e32 v113, 0x4b400000, v113
	v_add_f32_e32 v114, 0x4b400000, v114
	v_add_f32_e32 v115, 0x4b400000, v115
	v_perm_b32 v108, v111, v108, s45
	v_perm_b32 v109, v110, v109, s46
	v_or_b32_e32 v176, v108, v109
	v_perm_b32 v112, v115, v112, s45
	v_perm_b32 v113, v114, v113, s46
	v_or_b32_e32 v177, v112, v113
	global_store_dwordx2 v1, v[176:177], s[42:43] offset:512
	v_cvt_pk_bf16_f32 v254, v116, v117
	v_cvt_pk_bf16_f32 v255, v118, v119
	v_cvt_pk_bf16_f32 v94, v120, v121
	v_cvt_pk_bf16_f32 v95, v122, v123
	global_store_dwordx2 v78, v[254:255], s[38:39] offset:2048
	global_store_dwordx2 v78, v[94:95], s[38:39] offset:2056
	v_mul_f32_e32 v116, 0x41fe0000, v116
	v_mul_f32_e32 v117, 0x41fe0000, v117
	v_mul_f32_e32 v118, 0x41fe0000, v118
	v_mul_f32_e32 v119, 0x41fe0000, v119
	v_mul_f32_e32 v120, 0x41fe0000, v120
	v_mul_f32_e32 v121, 0x41fe0000, v121
	v_mul_f32_e32 v122, 0x41fe0000, v122
	v_mul_f32_e32 v123, 0x41fe0000, v123
	v_med3_f32 v116, v116, s44, v203
	v_med3_f32 v117, v117, s44, v203
	v_med3_f32 v118, v118, s44, v203
	v_med3_f32 v119, v119, s44, v203
	v_med3_f32 v120, v120, s44, v203
	v_med3_f32 v121, v121, s44, v203
	v_med3_f32 v122, v122, s44, v203
	v_med3_f32 v123, v123, s44, v203
	v_add_f32_e32 v116, 0x4b400000, v116
	v_add_f32_e32 v117, 0x4b400000, v117
	v_add_f32_e32 v118, 0x4b400000, v118
	v_add_f32_e32 v119, 0x4b400000, v119
	v_add_f32_e32 v120, 0x4b400000, v120
	v_add_f32_e32 v121, 0x4b400000, v121
	v_add_f32_e32 v122, 0x4b400000, v122
	v_add_f32_e32 v123, 0x4b400000, v123
	v_perm_b32 v116, v119, v116, s45
	v_perm_b32 v117, v118, v117, s46
	v_or_b32_e32 v176, v116, v117
	v_perm_b32 v120, v123, v120, s45
	v_perm_b32 v121, v122, v121, s46
	v_or_b32_e32 v177, v120, v121
	global_store_dwordx2 v1, v[176:177], s[42:43] offset:1024
	v_cvt_pk_bf16_f32 v254, v124, v125
	v_cvt_pk_bf16_f32 v255, v126, v127
	v_cvt_pk_bf16_f32 v94, v128, v129
	v_cvt_pk_bf16_f32 v95, v130, v131
	global_store_dwordx2 v78, v[254:255], s[38:39] offset:3072
	global_store_dwordx2 v78, v[94:95], s[38:39] offset:3080
	v_mul_f32_e32 v124, 0x41fe0000, v124
	v_mul_f32_e32 v125, 0x41fe0000, v125
	v_mul_f32_e32 v126, 0x41fe0000, v126
	v_mul_f32_e32 v127, 0x41fe0000, v127
	v_mul_f32_e32 v128, 0x41fe0000, v128
	v_mul_f32_e32 v129, 0x41fe0000, v129
	v_mul_f32_e32 v130, 0x41fe0000, v130
	v_mul_f32_e32 v131, 0x41fe0000, v131
	v_med3_f32 v124, v124, s44, v203
	v_med3_f32 v125, v125, s44, v203
	v_med3_f32 v126, v126, s44, v203
	v_med3_f32 v127, v127, s44, v203
	v_med3_f32 v128, v128, s44, v203
	v_med3_f32 v129, v129, s44, v203
	v_med3_f32 v130, v130, s44, v203
	v_med3_f32 v131, v131, s44, v203
	v_add_f32_e32 v124, 0x4b400000, v124
	v_add_f32_e32 v125, 0x4b400000, v125
	v_add_f32_e32 v126, 0x4b400000, v126
	v_add_f32_e32 v127, 0x4b400000, v127
	v_add_f32_e32 v128, 0x4b400000, v128
	v_add_f32_e32 v129, 0x4b400000, v129
	v_add_f32_e32 v130, 0x4b400000, v130
	v_add_f32_e32 v131, 0x4b400000, v131
	v_perm_b32 v124, v127, v124, s45
	v_perm_b32 v125, v126, v125, s46
	v_or_b32_e32 v176, v124, v125
	v_perm_b32 v128, v131, v128, s45
	v_perm_b32 v129, v130, v129, s46
	v_or_b32_e32 v177, v128, v129
	global_store_dwordx2 v1, v[176:177], s[42:43] offset:1536
	v_cvt_pk_bf16_f32 v254, v132, v133
	v_cvt_pk_bf16_f32 v255, v134, v135
	v_cvt_pk_bf16_f32 v94, v136, v137
	v_cvt_pk_bf16_f32 v95, v138, v139
	global_store_dwordx2 v241, v[254:255], s[38:39]
	global_store_dwordx2 v241, v[94:95], s[38:39] offset:8
	v_mul_f32_e32 v132, 0x41fe0000, v132
	v_mul_f32_e32 v133, 0x41fe0000, v133
; __device__ __forceinline__ unsigned pk2(float lo, float hi) { return cvt_pk_bf16(lo, hi); }
; __device__ __forceinline__ unsigned pk4_i8(float a, float b, float c, float d, float s) {
;     const unsigned ua = __float_as_uint(__builtin_amdgcn_fmed3f(a * s, -127.f, 127.f) + 12582912.f), ub = __float_as_uint(__builtin_amdgcn_fmed3f(b * s, -127.f, 127.f) + 12582912.f);
;     const unsigned uc = __float_as_uint(__builtin_amdgcn_fmed3f(c * s, -127.f, 127.f) + 12582912.f), ud = __float_as_uint(__builtin_amdgcn_fmed3f(d * s, -127.f, 127.f) + 12582912.f);
;     return (ua & 0xffu) | ((ub & 0xffu) << 8) | ((uc & 0xffu) << 16) | (ud << 24);
; template <bool WRITE_BF, bool WRITE_F32, bool WRITE_F8 = false>
; __device__ __forceinline__ void ln_phase(Frame& F, const bf16* T, const float* g, const float* b, unsigned char* x8 = nullptr) {
;     ...
;         for (int j = 0; j < 8; ++j) { const int c0 = 8 * (lane_ + 64 * j);
;             const f32x4 g0 = *(const f32x4*)(g + c0), g1 = *(const f32x4*)(g + c0 + 4), b0 = *(const f32x4*)(b + c0), b1 = *(const f32x4*)(b + c0 + 4);
;             const f32x4 y0 = (f32x4){v[8 * j], v[8 * j + 1], v[8 * j + 2], v[8 * j + 3]} * rstd * g0 + b0, y1 = (f32x4){v[8 * j + 4], v[8 * j + 5], v[8 * j + 6], v[8 * j + 7]} * rstd * g1 + b1;
;             if (WRITE_F32) { *(f32x4*)(Y + (size_t)row * D + c0) = y0; *(f32x4*)(Y + (size_t)row * D + c0 + 4) = y1; }
;             if (WRITE_BF) *(u32x4*)(xb + (size_t)row * D + c0) = (u32x4){pk2(y0[0], y0[1]), pk2(y0[2], y0[3]), pk2(y1[0], y1[1]), pk2(y1[2], y1[3])};
;             if (WRITE_F8) *(u32x2*)(x8 + (size_t)row * D + c0) = (u32x2){pk4_i8(y0[0], y0[1], y0[2], y0[3], I8_ACT), pk4_i8(y1[0], y1[1], y1[2], y1[3], I8_ACT)}; }
;     }
	v_mul_f32_e32 v134, 0x41fe0000, v134
	v_mul_f32_e32 v135, 0x41fe0000, v135
	v_mul_f32_e32 v136, 0x41fe0000, v136
	v_mul_f32_e32 v137, 0x41fe0000, v137
	v_mul_f32_e32 v138, 0x41fe0000, v138
	v_mul_f32_e32 v139, 0x41fe0000, v139
	v_med3_f32 v132, v132, s44, v203
	v_med3_f32 v133, v133, s44, v203
	v_med3_f32 v134, v134, s44, v203
	v_med3_f32 v135, v135, s44, v203
	v_med3_f32 v136, v136, s44, v203
	v_med3_f32 v137, v137, s44, v203
	v_med3_f32 v138, v138, s44, v203
	v_med3_f32 v139, v139, s44, v203
	v_add_f32_e32 v132, 0x4b400000, v132
	v_add_f32_e32 v133, 0x4b400000, v133
	v_add_f32_e32 v134, 0x4b400000, v134
	v_add_f32_e32 v135, 0x4b400000, v135
	v_add_f32_e32 v136, 0x4b400000, v136
	v_add_f32_e32 v137, 0x4b400000, v137
	v_add_f32_e32 v138, 0x4b400000, v138
	v_add_f32_e32 v139, 0x4b400000, v139
	v_perm_b32 v132, v135, v132, s45
	v_perm_b32 v133, v134, v133, s46
	v_or_b32_e32 v176, v132, v133
	v_perm_b32 v136, v139, v136, s45
	v_perm_b32 v137, v138, v137, s46
	v_or_b32_e32 v177, v136, v137
	global_store_dwordx2 v1, v[176:177], s[42:43] offset:2048
	v_cvt_pk_bf16_f32 v254, v140, v141
	v_cvt_pk_bf16_f32 v255, v142, v143
	v_cvt_pk_bf16_f32 v94, v144, v145
	v_cvt_pk_bf16_f32 v95, v146, v147
	global_store_dwordx2 v241, v[254:255], s[38:39] offset:1024
	global_store_dwordx2 v241, v[94:95], s[38:39] offset:1032
	v_mul_f32_e32 v140, 0x41fe0000, v140
	v_mul_f32_e32 v141, 0x41fe0000, v141
	v_mul_f32_e32 v142, 0x41fe0000, v142
	v_mul_f32_e32 v143, 0x41fe0000, v143
	v_mul_f32_e32 v144, 0x41fe0000, v144
	v_mul_f32_e32 v145, 0x41fe0000, v145
	v_mul_f32_e32 v146, 0x41fe0000, v146
	v_mul_f32_e32 v147, 0x41fe0000, v147
	v_med3_f32 v140, v140, s44, v203
	v_med3_f32 v141, v141, s44, v203
	v_med3_f32 v142, v142, s44, v203
	v_med3_f32 v143, v143, s44, v203
	v_med3_f32 v144, v144, s44, v203
	v_med3_f32 v145, v145, s44, v203
	v_med3_f32 v146, v146, s44, v203
	v_med3_f32 v147, v147, s44, v203
	v_add_f32_e32 v140, 0x4b400000, v140
	v_add_f32_e32 v141, 0x4b400000, v141
	v_add_f32_e32 v142, 0x4b400000, v142
	v_add_f32_e32 v143, 0x4b400000, v143
	v_add_f32_e32 v144, 0x4b400000, v144
	v_add_f32_e32 v145, 0x4b400000, v145
	v_add_f32_e32 v146, 0x4b400000, v146
	v_add_f32_e32 v147, 0x4b400000, v147
	v_perm_b32 v140, v143, v140, s45
	v_perm_b32 v141, v142, v141, s46
	v_or_b32_e32 v176, v140, v141
	v_perm_b32 v144, v147, v144, s45
	v_perm_b32 v145, v146, v145, s46
	v_or_b32_e32 v177, v144, v145
	global_store_dwordx2 v1, v[176:177], s[42:43] offset:2560
	v_cvt_pk_bf16_f32 v254, v148, v149
	v_cvt_pk_bf16_f32 v255, v150, v151
	v_cvt_pk_bf16_f32 v94, v152, v153
	v_cvt_pk_bf16_f32 v95, v154, v155
	global_store_dwordx2 v241, v[254:255], s[38:39] offset:2048
	global_store_dwordx2 v241, v[94:95], s[38:39] offset:2056
	v_mul_f32_e32 v148, 0x41fe0000, v148
	v_mul_f32_e32 v149, 0x41fe0000, v149
	v_mul_f32_e32 v150, 0x41fe0000, v150
	v_mul_f32_e32 v151, 0x41fe0000, v151
	v_mul_f32_e32 v152, 0x41fe0000, v152
	v_mul_f32_e32 v153, 0x41fe0000, v153
	v_mul_f32_e32 v154, 0x41fe0000, v154
	v_mul_f32_e32 v155, 0x41fe0000, v155
	v_med3_f32 v148, v148, s44, v203
	v_med3_f32 v149, v149, s44, v203
	v_med3_f32 v150, v150, s44, v203
	v_med3_f32 v151, v151, s44, v203
	v_med3_f32 v152, v152, s44, v203
	v_med3_f32 v153, v153, s44, v203
	v_med3_f32 v154, v154, s44, v203
	v_med3_f32 v155, v155, s44, v203
	v_add_f32_e32 v148, 0x4b400000, v148
	v_add_f32_e32 v149, 0x4b400000, v149
	v_add_f32_e32 v150, 0x4b400000, v150
	v_add_f32_e32 v151, 0x4b400000, v151
	v_add_f32_e32 v152, 0x4b400000, v152
	v_add_f32_e32 v153, 0x4b400000, v153
	v_add_f32_e32 v154, 0x4b400000, v154
	v_add_f32_e32 v155, 0x4b400000, v155
	v_perm_b32 v148, v151, v148, s45
	v_perm_b32 v149, v150, v149, s46
	v_or_b32_e32 v176, v148, v149
	v_perm_b32 v152, v155, v152, s45
	v_perm_b32 v153, v154, v153, s46
	v_or_b32_e32 v177, v152, v153
	global_store_dwordx2 v1, v[176:177], s[42:43] offset:3072
	v_cvt_pk_bf16_f32 v254, v204, v205
	v_cvt_pk_bf16_f32 v255, v206, v207
	v_cvt_pk_bf16_f32 v94, v208, v209
	v_cvt_pk_bf16_f32 v95, v210, v211
	global_store_dwordx2 v241, v[254:255], s[38:39] offset:3072
	global_store_dwordx2 v241, v[94:95], s[38:39] offset:3080
	v_mul_f32_e32 v204, 0x41fe0000, v204
	v_mul_f32_e32 v205, 0x41fe0000, v205
	v_mul_f32_e32 v206, 0x41fe0000, v206
	v_mul_f32_e32 v207, 0x41fe0000, v207
	v_mul_f32_e32 v208, 0x41fe0000, v208
	v_mul_f32_e32 v209, 0x41fe0000, v209
	v_mul_f32_e32 v210, 0x41fe0000, v210
	v_mul_f32_e32 v211, 0x41fe0000, v211
	v_med3_f32 v204, v204, s44, v203
	v_med3_f32 v205, v205, s44, v203
	v_med3_f32 v206, v206, s44, v203
	v_med3_f32 v207, v207, s44, v203
	v_med3_f32 v208, v208, s44, v203
	v_med3_f32 v209, v209, s44, v203
	v_med3_f32 v210, v210, s44, v203
	v_med3_f32 v211, v211, s44, v203
	v_add_f32_e32 v204, 0x4b400000, v204
	v_add_f32_e32 v205, 0x4b400000, v205
	v_add_f32_e32 v206, 0x4b400000, v206
	v_add_f32_e32 v207, 0x4b400000, v207
	v_add_f32_e32 v208, 0x4b400000, v208
	v_add_f32_e32 v209, 0x4b400000, v209
	v_add_f32_e32 v210, 0x4b400000, v210
	v_add_f32_e32 v211, 0x4b400000, v211
	v_perm_b32 v204, v207, v204, s45
	v_perm_b32 v205, v206, v205, s46
	v_or_b32_e32 v176, v204, v205
	v_perm_b32 v208, v211, v208, s45
	v_perm_b32 v209, v210, v209, s46
	v_or_b32_e32 v177, v208, v209
	global_store_dwordx2 v1, v[176:177], s[42:43] offset:3584
	s_add_i32 s41, s41, s92
	s_cmpk_lt_i32 s41, 0x4080
	s_cbranch_scc1 .Lln1_row
	s_branch .LBB0_318

; template <bool WRITE_BF, bool WRITE_F32, bool WRITE_F8 = false>
; __device__ __forceinline__ void ln_phase(Frame& F, const bf16* T, const float* g, const float* b, unsigned char* x8 = nullptr) {
;     float* Y = F.out; bf16* xb = (bf16*)(F.ws + WS_XB);
;     int lane_ = threadIdx.x & 63; asm volatile("" : "+v"(lane_));
;     for (int row = F.gw; row < MR; row += F.NGW) {
;         const u32x4* tr = (const u32x4*)(T + (size_t)row * D) + lane_;
;         float v[64]; float s = 0.f;
; #pragma unroll
;         for (int j = 0; j < 8; ++j) { const u32x4 w = tr[64 * j];
; #pragma unroll
;             for (int q = 0; q < 4; ++q) { v[8 * j + 2 * q] = __uint_as_float(w[q] << 16); v[8 * j + 2 * q + 1] = __uint_as_float(w[q] & 0xffff0000u); s += v[8 * j + 2 * q] + v[8 * j + 2 * q + 1]; } }
.LBB0_1439:
	s_load_dwordx4 s[4:7], s[74:75], 0x48
	s_load_dwordx4 s[52:55], s[74:75], 0x100
	v_mbcnt_lo_u32_b32 v203, -1, 0
	v_mbcnt_hi_u32_b32 v203, -1, v203
	v_lshlrev_b32_e32 v78, 4, v203
	v_add_u32_e32 v241, 0x1000, v78
	v_lshlrev_b32_e32 v1, 3, v203
	v_lshlrev_b32_e32 v92, 5, v203
	v_add_u32_e32 v24, 0x1000, v92
	v_add_u32_e32 v169, 0x2000, v92
	v_add_u32_e32 v179, 0x3000, v92
	s_waitcnt lgkmcnt(0)
	global_load_dwordx4 v[212:215], v92, s[4:5]
	global_load_dwordx4 v[216:219], v92, s[4:5] offset:16
	global_load_dwordx4 v[186:189], v92, s[6:7]
	global_load_dwordx4 v[190:193], v92, s[6:7] offset:16
	global_load_dwordx4 v[220:223], v92, s[4:5] offset:2048
	global_load_dwordx4 v[224:227], v92, s[4:5] offset:2064
	global_load_dwordx4 v[194:197], v92, s[6:7] offset:2048
	global_load_dwordx4 v[198:201], v92, s[6:7] offset:2064
	global_load_dwordx4 v[228:231], v24, s[4:5]
	global_load_dwordx4 v[232:235], v24, s[4:5] offset:16
	global_load_dwordx4 v[242:245], v24, s[6:7]
	global_load_dwordx4 v[246:249], v24, s[6:7] offset:16
	global_load_dwordx4 v[236:239], v24, s[4:5] offset:2048
	global_load_dwordx4 v[46:49], v24, s[4:5] offset:2064
	global_load_dwordx4 v[250:253], v24, s[6:7] offset:2048
	global_load_dwordx4 v[2:5], v24, s[6:7] offset:2064
	global_load_dwordx4 v[50:53], v169, s[4:5]
	global_load_dwordx4 v[54:57], v169, s[4:5] offset:16
	global_load_dwordx4 v[6:9], v169, s[6:7]
	global_load_dwordx4 v[10:13], v169, s[6:7] offset:16
	global_load_dwordx4 v[58:61], v169, s[4:5] offset:2048
	global_load_dwordx4 v[62:65], v169, s[4:5] offset:2064
	global_load_dwordx4 v[14:17], v169, s[6:7] offset:2048
	global_load_dwordx4 v[80:83], v169, s[6:7] offset:2064
	global_load_dwordx4 v[66:69], v179, s[4:5]
	global_load_dwordx4 v[70:73], v179, s[4:5] offset:16
	global_load_dwordx4 v[84:87], v179, s[6:7]
	global_load_dwordx4 v[88:91], v179, s[6:7] offset:16
	global_load_dwordx4 v[74:77], v179, s[4:5] offset:2048
	global_load_dwordx4 v[182:185], v179, s[4:5] offset:2064
	global_load_dwordx4 v[172:175], v179, s[6:7] offset:2048
	global_load_dwordx4 v[156:159], v179, s[6:7] offset:2064
	s_add_u32 s34, s54, 0x18500000
	s_addc_u32 s35, s55, 0
	s_mov_b32 s41, s94
.Lln2_row:
	s_lshl_b32 s36, s41, 13
	s_add_u32 s36, s34, s36
	s_addc_u32 s37, s35, 0
	global_load_dwordx4 v[104:107], v78, s[36:37]
	global_load_dwordx4 v[112:115], v78, s[36:37] offset:1024
	global_load_dwordx4 v[120:123], v78, s[36:37] offset:2048
	global_load_dwordx4 v[128:131], v78, s[36:37] offset:3072
	global_load_dwordx4 v[136:139], v241, s[36:37]
	global_load_dwordx4 v[144:147], v241, s[36:37] offset:1024
	global_load_dwordx4 v[152:155], v241, s[36:37] offset:2048
	global_load_dwordx4 v[208:211], v241, s[36:37] offset:3072
	v_mov_b32_e32 v160, 0
	v_mov_b32_e32 v161, 0
	s_waitcnt vmcnt(0)
	v_lshlrev_b32_e32 v100, 16, v104
	v_and_b32_e32 v101, 0xffff0000, v104
	v_lshlrev_b32_e32 v102, 16, v105
	v_and_b32_e32 v103, 0xffff0000, v105
	v_lshlrev_b32_e32 v104, 16, v106
	v_and_b32_e32 v105, 0xffff0000, v106
	v_lshlrev_b32_e32 v106, 16, v107
	v_and_b32_e32 v107, 0xffff0000, v107
	v_pk_add_f32 v[160:161], v[160:161], v[100:101]
	v_pk_add_f32 v[160:161], v[160:161], v[102:103]
	v_pk_add_f32 v[160:161], v[160:161], v[104:105]
	v_pk_add_f32 v[160:161], v[160:161], v[106:107]
	v_lshlrev_b32_e32 v108, 16, v112
	v_and_b32_e32 v109, 0xffff0000, v112
	v_lshlrev_b32_e32 v110, 16, v113
	v_and_b32_e32 v111, 0xffff0000, v113
	v_lshlrev_b32_e32 v112, 16, v114
	v_and_b32_e32 v113, 0xffff0000, v114
	v_lshlrev_b32_e32 v114, 16, v115
	v_and_b32_e32 v115, 0xffff0000, v115
	v_pk_add_f32 v[160:161], v[160:161], v[108:109]
	v_pk_add_f32 v[160:161], v[160:161], v[110:111]
	v_pk_add_f32 v[160:161], v[160:161], v[112:113]
	v_pk_add_f32 v[160:161], v[160:161], v[114:115]
	v_lshlrev_b32_e32 v116, 16, v120
	v_and_b32_e32 v117, 0xffff0000, v120
	v_lshlrev_b32_e32 v118, 16, v121
	v_and_b32_e32 v119, 0xffff0000, v121
	v_lshlrev_b32_e32 v120, 16, v122
	v_and_b32_e32 v121, 0xffff0000, v122
	v_lshlrev_b32_e32 v122, 16, v123
	v_and_b32_e32 v123, 0xffff0000, v123
	v_pk_add_f32 v[160:161], v[160:161], v[116:117]
	v_pk_add_f32 v[160:161], v[160:161], v[118:119]
	v_pk_add_f32 v[160:161], v[160:161], v[120:121]
	v_pk_add_f32 v[160:161], v[160:161], v[122:123]
	v_lshlrev_b32_e32 v124, 16, v128
	v_and_b32_e32 v125, 0xffff0000, v128
	v_lshlrev_b32_e32 v126, 16, v129
	v_and_b32_e32 v127, 0xffff0000, v129
	v_lshlrev_b32_e32 v128, 16, v130
	v_and_b32_e32 v129, 0xffff0000, v130
	v_lshlrev_b32_e32 v130, 16, v131
	v_and_b32_e32 v131, 0xffff0000, v131
	v_pk_add_f32 v[160:161], v[160:161], v[124:125]
	v_pk_add_f32 v[160:161], v[160:161], v[126:127]
	v_pk_add_f32 v[160:161], v[160:161], v[128:129]
	v_pk_add_f32 v[160:161], v[160:161], v[130:131]
	v_lshlrev_b32_e32 v132, 16, v136
	v_and_b32_e32 v133, 0xffff0000, v136
	v_lshlrev_b32_e32 v134, 16, v137
	v_and_b32_e32 v135, 0xffff0000, v137
	v_lshlrev_b32_e32 v136, 16, v138
	v_and_b32_e32 v137, 0xffff0000, v138
	v_lshlrev_b32_e32 v138, 16, v139
	v_and_b32_e32 v139, 0xffff0000, v139
	v_pk_add_f32 v[160:161], v[160:161], v[132:133]
	v_pk_add_f32 v[160:161], v[160:161], v[134:135]
	v_pk_add_f32 v[160:161], v[160:161], v[136:137]
	v_pk_add_f32 v[160:161], v[160:161], v[138:139]
	v_lshlrev_b32_e32 v140, 16, v144
	v_and_b32_e32 v141, 0xffff0000, v144
	v_lshlrev_b32_e32 v142, 16, v145
	v_and_b32_e32 v143, 0xffff0000, v145
	v_lshlrev_b32_e32 v144, 16, v146
	v_and_b32_e32 v145, 0xffff0000, v146
	v_lshlrev_b32_e32 v146, 16, v147
	v_and_b32_e32 v147, 0xffff0000, v147
	v_pk_add_f32 v[160:161], v[160:161], v[140:141]
	v_pk_add_f32 v[160:161], v[160:161], v[142:143]
	v_pk_add_f32 v[160:161], v[160:161], v[144:145]
; template <bool WRITE_BF, bool WRITE_F32, bool WRITE_F8 = false>
; __device__ __forceinline__ void ln_phase(Frame& F, const bf16* T, const float* g, const float* b, unsigned char* x8 = nullptr) {
;     ...
;             for (int q = 0; q < 4; ++q) { v[8 * j + 2 * q] = __uint_as_float(w[q] << 16); v[8 * j + 2 * q + 1] = __uint_as_float(w[q] & 0xffff0000u); s += v[8 * j + 2 * q] + v[8 * j + 2 * q + 1]; } }
;         const float mean = wave_sum(s) * (1.f / D); float s2 = 0.f;
; #pragma unroll
;         for (int i = 0; i < 64; ++i) { v[i] -= mean; s2 += v[i] * v[i]; }
	v_pk_add_f32 v[160:161], v[160:161], v[146:147]
	v_lshlrev_b32_e32 v148, 16, v152
	v_and_b32_e32 v149, 0xffff0000, v152
	v_lshlrev_b32_e32 v150, 16, v153
	v_and_b32_e32 v151, 0xffff0000, v153
	v_lshlrev_b32_e32 v152, 16, v154
	v_and_b32_e32 v153, 0xffff0000, v154
	v_lshlrev_b32_e32 v154, 16, v155
	v_and_b32_e32 v155, 0xffff0000, v155
	v_pk_add_f32 v[160:161], v[160:161], v[148:149]
	v_pk_add_f32 v[160:161], v[160:161], v[150:151]
	v_pk_add_f32 v[160:161], v[160:161], v[152:153]
	v_pk_add_f32 v[160:161], v[160:161], v[154:155]
	v_lshlrev_b32_e32 v204, 16, v208
	v_and_b32_e32 v205, 0xffff0000, v208
	v_lshlrev_b32_e32 v206, 16, v209
	v_and_b32_e32 v207, 0xffff0000, v209
	v_lshlrev_b32_e32 v208, 16, v210
	v_and_b32_e32 v209, 0xffff0000, v210
	v_lshlrev_b32_e32 v210, 16, v211
	v_and_b32_e32 v211, 0xffff0000, v211
	v_pk_add_f32 v[160:161], v[160:161], v[204:205]
	v_pk_add_f32 v[160:161], v[160:161], v[206:207]
	v_pk_add_f32 v[160:161], v[160:161], v[208:209]
	v_pk_add_f32 v[160:161], v[160:161], v[210:211]
	v_add_f32_e32 v99, v160, v161
	s_nop 1
	v_add_f32_dpp v99, v99, v99 quad_perm:[1,0,3,2] row_mask:0xf bank_mask:0xf
	s_nop 1
	v_add_f32_dpp v99, v99, v99 quad_perm:[2,3,0,1] row_mask:0xf bank_mask:0xf
	s_nop 1
	v_add_f32_dpp v99, v99, v99 row_half_mirror row_mask:0xf bank_mask:0xf
	s_nop 1
	v_add_f32_dpp v99, v99, v99 row_mirror row_mask:0xf bank_mask:0xf
	s_nop 1
	v_readlane_b32 s28, v99, 0
	v_readlane_b32 s29, v99, 16
	v_readlane_b32 s30, v99, 32
	v_readlane_b32 s31, v99, 48
	s_nop 1
	v_mov_b32_e32 v99, s28
	v_add_f32_e32 v99, s29, v99
	v_add_f32_e32 v203, s30, v99
	v_add_f32_e32 v99, s31, v203
	v_mul_f32_e32 v18, 0xb9800000, v99
	v_mov_b32_e32 v160, 0
	v_mov_b32_e32 v161, 0
	v_pk_add_f32 v[100:101], v[100:101], v[18:19] op_sel_hi:[1,0]
	v_pk_add_f32 v[102:103], v[102:103], v[18:19] op_sel_hi:[1,0]
	v_pk_add_f32 v[104:105], v[104:105], v[18:19] op_sel_hi:[1,0]
	v_pk_add_f32 v[106:107], v[106:107], v[18:19] op_sel_hi:[1,0]
	v_pk_add_f32 v[108:109], v[108:109], v[18:19] op_sel_hi:[1,0]
	v_pk_add_f32 v[110:111], v[110:111], v[18:19] op_sel_hi:[1,0]
	v_pk_add_f32 v[112:113], v[112:113], v[18:19] op_sel_hi:[1,0]
	v_pk_add_f32 v[114:115], v[114:115], v[18:19] op_sel_hi:[1,0]
	v_pk_add_f32 v[116:117], v[116:117], v[18:19] op_sel_hi:[1,0]
	v_pk_add_f32 v[118:119], v[118:119], v[18:19] op_sel_hi:[1,0]
	v_pk_add_f32 v[120:121], v[120:121], v[18:19] op_sel_hi:[1,0]
	v_pk_add_f32 v[122:123], v[122:123], v[18:19] op_sel_hi:[1,0]
	v_pk_add_f32 v[124:125], v[124:125], v[18:19] op_sel_hi:[1,0]
	v_pk_add_f32 v[126:127], v[126:127], v[18:19] op_sel_hi:[1,0]
	v_pk_add_f32 v[128:129], v[128:129], v[18:19] op_sel_hi:[1,0]
	v_pk_add_f32 v[130:131], v[130:131], v[18:19] op_sel_hi:[1,0]
	v_pk_add_f32 v[132:133], v[132:133], v[18:19] op_sel_hi:[1,0]
	v_pk_add_f32 v[134:135], v[134:135], v[18:19] op_sel_hi:[1,0]
	v_pk_add_f32 v[136:137], v[136:137], v[18:19] op_sel_hi:[1,0]
	v_pk_add_f32 v[138:139], v[138:139], v[18:19] op_sel_hi:[1,0]
	v_pk_add_f32 v[140:141], v[140:141], v[18:19] op_sel_hi:[1,0]
	v_pk_add_f32 v[142:143], v[142:143], v[18:19] op_sel_hi:[1,0]
	v_pk_add_f32 v[144:145], v[144:145], v[18:19] op_sel_hi:[1,0]
	v_pk_add_f32 v[146:147], v[146:147], v[18:19] op_sel_hi:[1,0]
	v_pk_add_f32 v[148:149], v[148:149], v[18:19] op_sel_hi:[1,0]
	v_pk_add_f32 v[150:151], v[150:151], v[18:19] op_sel_hi:[1,0]
	v_pk_add_f32 v[152:153], v[152:153], v[18:19] op_sel_hi:[1,0]
	v_pk_add_f32 v[154:155], v[154:155], v[18:19] op_sel_hi:[1,0]
	v_pk_add_f32 v[204:205], v[204:205], v[18:19] op_sel_hi:[1,0]
	v_pk_add_f32 v[206:207], v[206:207], v[18:19] op_sel_hi:[1,0]
	v_pk_add_f32 v[208:209], v[208:209], v[18:19] op_sel_hi:[1,0]
	v_pk_add_f32 v[210:211], v[210:211], v[18:19] op_sel_hi:[1,0]
	v_pk_fma_f32 v[160:161], v[100:101], v[100:101], v[160:161]
	v_pk_fma_f32 v[160:161], v[102:103], v[102:103], v[160:161]
	v_pk_fma_f32 v[160:161], v[104:105], v[104:105], v[160:161]
	v_pk_fma_f32 v[160:161], v[106:107], v[106:107], v[160:161]
	v_pk_fma_f32 v[160:161], v[108:109], v[108:109], v[160:161]
	v_pk_fma_f32 v[160:161], v[110:111], v[110:111], v[160:161]
	v_pk_fma_f32 v[160:161], v[112:113], v[112:113], v[160:161]
	v_pk_fma_f32 v[160:161], v[114:115], v[114:115], v[160:161]
	v_pk_fma_f32 v[160:161], v[116:117], v[116:117], v[160:161]
	v_pk_fma_f32 v[160:161], v[118:119], v[118:119], v[160:161]
	v_pk_fma_f32 v[160:161], v[120:121], v[120:121], v[160:161]
	v_pk_fma_f32 v[160:161], v[122:123], v[122:123], v[160:161]
	v_pk_fma_f32 v[160:161], v[124:125], v[124:125], v[160:161]
	v_pk_fma_f32 v[160:161], v[126:127], v[126:127], v[160:161]
	v_pk_fma_f32 v[160:161], v[128:129], v[128:129], v[160:161]
	v_pk_fma_f32 v[160:161], v[130:131], v[130:131], v[160:161]
	v_pk_fma_f32 v[160:161], v[132:133], v[132:133], v[160:161]
	v_pk_fma_f32 v[160:161], v[134:135], v[134:135], v[160:161]
	v_pk_fma_f32 v[160:161], v[136:137], v[136:137], v[160:161]
	v_pk_fma_f32 v[160:161], v[138:139], v[138:139], v[160:161]
	v_pk_fma_f32 v[160:161], v[140:141], v[140:141], v[160:161]
	v_pk_fma_f32 v[160:161], v[142:143], v[142:143], v[160:161]
	v_pk_fma_f32 v[160:161], v[144:145], v[144:145], v[160:161]
	v_pk_fma_f32 v[160:161], v[146:147], v[146:147], v[160:161]
	v_pk_fma_f32 v[160:161], v[148:149], v[148:149], v[160:161]
	v_pk_fma_f32 v[160:161], v[150:151], v[150:151], v[160:161]
	v_pk_fma_f32 v[160:161], v[152:153], v[152:153], v[160:161]
	v_pk_fma_f32 v[160:161], v[154:155], v[154:155], v[160:161]
	v_pk_fma_f32 v[160:161], v[204:205], v[204:205], v[160:161]
	v_pk_fma_f32 v[160:161], v[206:207], v[206:207], v[160:161]
	v_pk_fma_f32 v[160:161], v[208:209], v[208:209], v[160:161]
; __device__ __forceinline__ unsigned pk2(float lo, float hi) { return cvt_pk_bf16(lo, hi); }
; template <bool WRITE_BF, bool WRITE_F32, bool WRITE_F8 = false>
; __device__ __forceinline__ void ln_phase(Frame& F, const bf16* T, const float* g, const float* b, unsigned char* x8 = nullptr) {
;     ...
;         for (int i = 0; i < 64; ++i) { v[i] -= mean; s2 += v[i] * v[i]; }
;         const float rstd = 1.f / sqrtf(wave_sum(s2) * (1.f / D) + 1e-5f);
; #pragma unroll
;         for (int j = 0; j < 8; ++j) { const int c0 = 8 * (lane_ + 64 * j);
;             const f32x4 g0 = *(const f32x4*)(g + c0), g1 = *(const f32x4*)(g + c0 + 4), b0 = *(const f32x4*)(b + c0), b1 = *(const f32x4*)(b + c0 + 4);
;             const f32x4 y0 = (f32x4){v[8 * j], v[8 * j + 1], v[8 * j + 2], v[8 * j + 3]} * rstd * g0 + b0, y1 = (f32x4){v[8 * j + 4], v[8 * j + 5], v[8 * j + 6], v[8 * j + 7]} * rstd * g1 + b1;
;             if (WRITE_F32) { *(f32x4*)(Y + (size_t)row * D + c0) = y0; *(f32x4*)(Y + (size_t)row * D + c0 + 4) = y1; }
;             if (WRITE_BF) *(u32x4*)(xb + (size_t)row * D + c0) = (u32x4){pk2(y0[0], y0[1]), pk2(y0[2], y0[3]), pk2(y1[0], y1[1]), pk2(y1[2], y1[3])};
	v_pk_fma_f32 v[160:161], v[210:211], v[210:211], v[160:161]
	v_add_f32_e32 v99, v160, v161
	s_nop 1
	v_add_f32_dpp v99, v99, v99 quad_perm:[1,0,3,2] row_mask:0xf bank_mask:0xf
	s_nop 1
	v_add_f32_dpp v99, v99, v99 quad_perm:[2,3,0,1] row_mask:0xf bank_mask:0xf
	s_nop 1
	v_add_f32_dpp v99, v99, v99 row_half_mirror row_mask:0xf bank_mask:0xf
	s_nop 1
	v_add_f32_dpp v99, v99, v99 row_mirror row_mask:0xf bank_mask:0xf
	s_nop 1
	v_readlane_b32 s28, v99, 0
	v_readlane_b32 s29, v99, 16
	v_readlane_b32 s30, v99, 32
	v_readlane_b32 s31, v99, 48
	s_nop 1
	v_mov_b32_e32 v99, s28
	v_add_f32_e32 v99, s29, v99
	v_add_f32_e32 v203, s30, v99
	v_add_f32_e32 v99, s31, v203
	v_mov_b32_e32 v203, 0x3727c5ac
	v_fmac_f32_e32 v203, 0x39800000, v99
	v_sqrt_f32_e32 v203, v203
	s_nop 0
	v_rcp_f32_e32 v18, v203
	s_nop 0
	v_pk_mul_f32 v[100:101], v[100:101], v[18:19] op_sel_hi:[1,0]
	v_pk_mul_f32 v[102:103], v[102:103], v[18:19] op_sel_hi:[1,0]
	v_pk_mul_f32 v[104:105], v[104:105], v[18:19] op_sel_hi:[1,0]
	v_pk_mul_f32 v[106:107], v[106:107], v[18:19] op_sel_hi:[1,0]
	v_pk_mul_f32 v[108:109], v[108:109], v[18:19] op_sel_hi:[1,0]
	v_pk_mul_f32 v[110:111], v[110:111], v[18:19] op_sel_hi:[1,0]
	v_pk_mul_f32 v[112:113], v[112:113], v[18:19] op_sel_hi:[1,0]
	v_pk_mul_f32 v[114:115], v[114:115], v[18:19] op_sel_hi:[1,0]
	v_pk_mul_f32 v[116:117], v[116:117], v[18:19] op_sel_hi:[1,0]
	v_pk_mul_f32 v[118:119], v[118:119], v[18:19] op_sel_hi:[1,0]
	v_pk_mul_f32 v[120:121], v[120:121], v[18:19] op_sel_hi:[1,0]
	v_pk_mul_f32 v[122:123], v[122:123], v[18:19] op_sel_hi:[1,0]
	v_pk_mul_f32 v[124:125], v[124:125], v[18:19] op_sel_hi:[1,0]
	v_pk_mul_f32 v[126:127], v[126:127], v[18:19] op_sel_hi:[1,0]
	v_pk_mul_f32 v[128:129], v[128:129], v[18:19] op_sel_hi:[1,0]
	v_pk_mul_f32 v[130:131], v[130:131], v[18:19] op_sel_hi:[1,0]
	v_pk_mul_f32 v[132:133], v[132:133], v[18:19] op_sel_hi:[1,0]
	v_pk_mul_f32 v[134:135], v[134:135], v[18:19] op_sel_hi:[1,0]
	v_pk_mul_f32 v[136:137], v[136:137], v[18:19] op_sel_hi:[1,0]
	v_pk_mul_f32 v[138:139], v[138:139], v[18:19] op_sel_hi:[1,0]
	v_pk_mul_f32 v[140:141], v[140:141], v[18:19] op_sel_hi:[1,0]
	v_pk_mul_f32 v[142:143], v[142:143], v[18:19] op_sel_hi:[1,0]
	v_pk_mul_f32 v[144:145], v[144:145], v[18:19] op_sel_hi:[1,0]
	v_pk_mul_f32 v[146:147], v[146:147], v[18:19] op_sel_hi:[1,0]
	v_pk_mul_f32 v[148:149], v[148:149], v[18:19] op_sel_hi:[1,0]
	v_pk_mul_f32 v[150:151], v[150:151], v[18:19] op_sel_hi:[1,0]
	v_pk_mul_f32 v[152:153], v[152:153], v[18:19] op_sel_hi:[1,0]
	v_pk_mul_f32 v[154:155], v[154:155], v[18:19] op_sel_hi:[1,0]
	v_pk_mul_f32 v[204:205], v[204:205], v[18:19] op_sel_hi:[1,0]
	v_pk_mul_f32 v[206:207], v[206:207], v[18:19] op_sel_hi:[1,0]
	v_pk_mul_f32 v[208:209], v[208:209], v[18:19] op_sel_hi:[1,0]
	v_pk_mul_f32 v[210:211], v[210:211], v[18:19] op_sel_hi:[1,0]
	v_pk_fma_f32 v[100:101], v[212:213], v[100:101], v[186:187]
	v_pk_fma_f32 v[102:103], v[214:215], v[102:103], v[188:189]
	v_pk_fma_f32 v[104:105], v[216:217], v[104:105], v[190:191]
	v_pk_fma_f32 v[106:107], v[218:219], v[106:107], v[192:193]
	v_pk_fma_f32 v[108:109], v[220:221], v[108:109], v[194:195]
	v_pk_fma_f32 v[110:111], v[222:223], v[110:111], v[196:197]
	v_pk_fma_f32 v[112:113], v[224:225], v[112:113], v[198:199]
	v_pk_fma_f32 v[114:115], v[226:227], v[114:115], v[200:201]
	v_pk_fma_f32 v[116:117], v[228:229], v[116:117], v[242:243]
	v_pk_fma_f32 v[118:119], v[230:231], v[118:119], v[244:245]
	v_pk_fma_f32 v[120:121], v[232:233], v[120:121], v[246:247]
	v_pk_fma_f32 v[122:123], v[234:235], v[122:123], v[248:249]
	v_pk_fma_f32 v[124:125], v[236:237], v[124:125], v[250:251]
	v_pk_fma_f32 v[126:127], v[238:239], v[126:127], v[252:253]
	v_pk_fma_f32 v[128:129], v[46:47], v[128:129], v[2:3]
	v_pk_fma_f32 v[130:131], v[48:49], v[130:131], v[4:5]
	v_pk_fma_f32 v[132:133], v[50:51], v[132:133], v[6:7]
	v_pk_fma_f32 v[134:135], v[52:53], v[134:135], v[8:9]
	v_pk_fma_f32 v[136:137], v[54:55], v[136:137], v[10:11]
	v_pk_fma_f32 v[138:139], v[56:57], v[138:139], v[12:13]
	v_pk_fma_f32 v[140:141], v[58:59], v[140:141], v[14:15]
	v_pk_fma_f32 v[142:143], v[60:61], v[142:143], v[16:17]
	v_pk_fma_f32 v[144:145], v[62:63], v[144:145], v[80:81]
	v_pk_fma_f32 v[146:147], v[64:65], v[146:147], v[82:83]
	v_pk_fma_f32 v[148:149], v[66:67], v[148:149], v[84:85]
	v_pk_fma_f32 v[150:151], v[68:69], v[150:151], v[86:87]
	v_pk_fma_f32 v[152:153], v[70:71], v[152:153], v[88:89]
	v_pk_fma_f32 v[154:155], v[72:73], v[154:155], v[90:91]
	v_pk_fma_f32 v[204:205], v[74:75], v[204:205], v[172:173]
	v_pk_fma_f32 v[206:207], v[76:77], v[206:207], v[174:175]
	v_pk_fma_f32 v[208:209], v[182:183], v[208:209], v[156:157]
	v_pk_fma_f32 v[210:211], v[184:185], v[210:211], v[158:159]
	s_lshl_b32 s38, s41, 13
	s_add_u32 s38, s54, s38
	s_addc_u32 s39, s55, 0
	s_add_u32 s38, s38, 0x100000
	s_addc_u32 s39, s39, 0
	s_lshl_b32 s42, s41, 12
	s_add_u32 s42, s54, s42
	s_addc_u32 s43, s55, 0
	s_add_u32 s42, s42, 0x49d00000
	s_addc_u32 s43, s43, 0
	v_mov_b32_e32 v203, 0x42fe0000
	s_mov_b32 s44, 0xc2fe0000
	s_mov_b32 s45, 0x040c0c00
	s_mov_b32 s46, 0x0c04000c
	v_cvt_pk_bf16_f32 v254, v100, v101
	v_cvt_pk_bf16_f32 v255, v102, v103
	v_cvt_pk_bf16_f32 v94, v104, v105
	v_cvt_pk_bf16_f32 v95, v106, v107
	global_store_dwordx2 v78, v[254:255], s[38:39]
	global_store_dwordx2 v78, v[94:95], s[38:39] offset:8
	v_mul_f32_e32 v100, 0x41fe0000, v100
	v_mul_f32_e32 v101, 0x41fe0000, v101
	v_mul_f32_e32 v102, 0x41fe0000, v102
	v_mul_f32_e32 v103, 0x41fe0000, v103
	v_mul_f32_e32 v104, 0x41fe0000, v104
	v_mul_f32_e32 v105, 0x41fe0000, v105
	v_mul_f32_e32 v106, 0x41fe0000, v106
	v_mul_f32_e32 v107, 0x41fe0000, v107
; __device__ __forceinline__ unsigned pk2(float lo, float hi) { return cvt_pk_bf16(lo, hi); }
; __device__ __forceinline__ unsigned pk4_i8(float a, float b, float c, float d, float s) {
;     const unsigned ua = __float_as_uint(__builtin_amdgcn_fmed3f(a * s, -127.f, 127.f) + 12582912.f), ub = __float_as_uint(__builtin_amdgcn_fmed3f(b * s, -127.f, 127.f) + 12582912.f);
;     const unsigned uc = __float_as_uint(__builtin_amdgcn_fmed3f(c * s, -127.f, 127.f) + 12582912.f), ud = __float_as_uint(__builtin_amdgcn_fmed3f(d * s, -127.f, 127.f) + 12582912.f);
;     return (ua & 0xffu) | ((ub & 0xffu) << 8) | ((uc & 0xffu) << 16) | (ud << 24);
; template <bool WRITE_BF, bool WRITE_F32, bool WRITE_F8 = false>
; __device__ __forceinline__ void ln_phase(Frame& F, const bf16* T, const float* g, const float* b, unsigned char* x8 = nullptr) {
;     ...
;         for (int j = 0; j < 8; ++j) { const int c0 = 8 * (lane_ + 64 * j);
;             const f32x4 g0 = *(const f32x4*)(g + c0), g1 = *(const f32x4*)(g + c0 + 4), b0 = *(const f32x4*)(b + c0), b1 = *(const f32x4*)(b + c0 + 4);
;             const f32x4 y0 = (f32x4){v[8 * j], v[8 * j + 1], v[8 * j + 2], v[8 * j + 3]} * rstd * g0 + b0, y1 = (f32x4){v[8 * j + 4], v[8 * j + 5], v[8 * j + 6], v[8 * j + 7]} * rstd * g1 + b1;
;             if (WRITE_F32) { *(f32x4*)(Y + (size_t)row * D + c0) = y0; *(f32x4*)(Y + (size_t)row * D + c0 + 4) = y1; }
;             if (WRITE_BF) *(u32x4*)(xb + (size_t)row * D + c0) = (u32x4){pk2(y0[0], y0[1]), pk2(y0[2], y0[3]), pk2(y1[0], y1[1]), pk2(y1[2], y1[3])};
;             if (WRITE_F8) *(u32x2*)(x8 + (size_t)row * D + c0) = (u32x2){pk4_i8(y0[0], y0[1], y0[2], y0[3], I8_ACT), pk4_i8(y1[0], y1[1], y1[2], y1[3], I8_ACT)}; }
	v_med3_f32 v100, v100, s44, v203
	v_med3_f32 v101, v101, s44, v203
	v_med3_f32 v102, v102, s44, v203
	v_med3_f32 v103, v103, s44, v203
	v_med3_f32 v104, v104, s44, v203
	v_med3_f32 v105, v105, s44, v203
	v_med3_f32 v106, v106, s44, v203
	v_med3_f32 v107, v107, s44, v203
	v_add_f32_e32 v100, 0x4b400000, v100
	v_add_f32_e32 v101, 0x4b400000, v101
	v_add_f32_e32 v102, 0x4b400000, v102
	v_add_f32_e32 v103, 0x4b400000, v103
	v_add_f32_e32 v104, 0x4b400000, v104
	v_add_f32_e32 v105, 0x4b400000, v105
	v_add_f32_e32 v106, 0x4b400000, v106
	v_add_f32_e32 v107, 0x4b400000, v107
	v_perm_b32 v100, v103, v100, s45
	v_perm_b32 v101, v102, v101, s46
	v_or_b32_e32 v176, v100, v101
	v_perm_b32 v104, v107, v104, s45
	v_perm_b32 v105, v106, v105, s46
	v_or_b32_e32 v177, v104, v105
	global_store_dwordx2 v1, v[176:177], s[42:43]
	v_cvt_pk_bf16_f32 v254, v108, v109
	v_cvt_pk_bf16_f32 v255, v110, v111
	v_cvt_pk_bf16_f32 v94, v112, v113
	v_cvt_pk_bf16_f32 v95, v114, v115
	global_store_dwordx2 v78, v[254:255], s[38:39] offset:1024
	global_store_dwordx2 v78, v[94:95], s[38:39] offset:1032
	v_mul_f32_e32 v108, 0x41fe0000, v108
	v_mul_f32_e32 v109, 0x41fe0000, v109
	v_mul_f32_e32 v110, 0x41fe0000, v110
	v_mul_f32_e32 v111, 0x41fe0000, v111
	v_mul_f32_e32 v112, 0x41fe0000, v112
	v_mul_f32_e32 v113, 0x41fe0000, v113
	v_mul_f32_e32 v114, 0x41fe0000, v114
	v_mul_f32_e32 v115, 0x41fe0000, v115
	v_med3_f32 v108, v108, s44, v203
	v_med3_f32 v109, v109, s44, v203
	v_med3_f32 v110, v110, s44, v203
	v_med3_f32 v111, v111, s44, v203
	v_med3_f32 v112, v112, s44, v203
	v_med3_f32 v113, v113, s44, v203
	v_med3_f32 v114, v114, s44, v203
	v_med3_f32 v115, v115, s44, v203
	v_add_f32_e32 v108, 0x4b400000, v108
	v_add_f32_e32 v109, 0x4b400000, v109
	v_add_f32_e32 v110, 0x4b400000, v110
	v_add_f32_e32 v111, 0x4b400000, v111
	v_add_f32_e32 v112, 0x4b400000, v112
	v_add_f32_e32 v113, 0x4b400000, v113
	v_add_f32_e32 v114, 0x4b400000, v114
	v_add_f32_e32 v115, 0x4b400000, v115
	v_perm_b32 v108, v111, v108, s45
	v_perm_b32 v109, v110, v109, s46
	v_or_b32_e32 v176, v108, v109
	v_perm_b32 v112, v115, v112, s45
	v_perm_b32 v113, v114, v113, s46
	v_or_b32_e32 v177, v112, v113
	global_store_dwordx2 v1, v[176:177], s[42:43] offset:512
	v_cvt_pk_bf16_f32 v254, v116, v117
	v_cvt_pk_bf16_f32 v255, v118, v119
	v_cvt_pk_bf16_f32 v94, v120, v121
	v_cvt_pk_bf16_f32 v95, v122, v123
	global_store_dwordx2 v78, v[254:255], s[38:39] offset:2048
	global_store_dwordx2 v78, v[94:95], s[38:39] offset:2056
	v_mul_f32_e32 v116, 0x41fe0000, v116
	v_mul_f32_e32 v117, 0x41fe0000, v117
	v_mul_f32_e32 v118, 0x41fe0000, v118
	v_mul_f32_e32 v119, 0x41fe0000, v119
	v_mul_f32_e32 v120, 0x41fe0000, v120
	v_mul_f32_e32 v121, 0x41fe0000, v121
	v_mul_f32_e32 v122, 0x41fe0000, v122
	v_mul_f32_e32 v123, 0x41fe0000, v123
	v_med3_f32 v116, v116, s44, v203
	v_med3_f32 v117, v117, s44, v203
	v_med3_f32 v118, v118, s44, v203
	v_med3_f32 v119, v119, s44, v203
	v_med3_f32 v120, v120, s44, v203
	v_med3_f32 v121, v121, s44, v203
	v_med3_f32 v122, v122, s44, v203
	v_med3_f32 v123, v123, s44, v203
	v_add_f32_e32 v116, 0x4b400000, v116
	v_add_f32_e32 v117, 0x4b400000, v117
	v_add_f32_e32 v118, 0x4b400000, v118
	v_add_f32_e32 v119, 0x4b400000, v119
	v_add_f32_e32 v120, 0x4b400000, v120
	v_add_f32_e32 v121, 0x4b400000, v121
	v_add_f32_e32 v122, 0x4b400000, v122
	v_add_f32_e32 v123, 0x4b400000, v123
	v_perm_b32 v116, v119, v116, s45
	v_perm_b32 v117, v118, v117, s46
	v_or_b32_e32 v176, v116, v117
	v_perm_b32 v120, v123, v120, s45
	v_perm_b32 v121, v122, v121, s46
	v_or_b32_e32 v177, v120, v121
	global_store_dwordx2 v1, v[176:177], s[42:43] offset:1024
	v_cvt_pk_bf16_f32 v254, v124, v125
	v_cvt_pk_bf16_f32 v255, v126, v127
	v_cvt_pk_bf16_f32 v94, v128, v129
	v_cvt_pk_bf16_f32 v95, v130, v131
	global_store_dwordx2 v78, v[254:255], s[38:39] offset:3072
	global_store_dwordx2 v78, v[94:95], s[38:39] offset:3080
	v_mul_f32_e32 v124, 0x41fe0000, v124
	v_mul_f32_e32 v125, 0x41fe0000, v125
	v_mul_f32_e32 v126, 0x41fe0000, v126
	v_mul_f32_e32 v127, 0x41fe0000, v127
	v_mul_f32_e32 v128, 0x41fe0000, v128
	v_mul_f32_e32 v129, 0x41fe0000, v129
	v_mul_f32_e32 v130, 0x41fe0000, v130
	v_mul_f32_e32 v131, 0x41fe0000, v131
	v_med3_f32 v124, v124, s44, v203
	v_med3_f32 v125, v125, s44, v203
	v_med3_f32 v126, v126, s44, v203
	v_med3_f32 v127, v127, s44, v203
	v_med3_f32 v128, v128, s44, v203
	v_med3_f32 v129, v129, s44, v203
	v_med3_f32 v130, v130, s44, v203
	v_med3_f32 v131, v131, s44, v203
	v_add_f32_e32 v124, 0x4b400000, v124
	v_add_f32_e32 v125, 0x4b400000, v125
	v_add_f32_e32 v126, 0x4b400000, v126
	v_add_f32_e32 v127, 0x4b400000, v127
	v_add_f32_e32 v128, 0x4b400000, v128
	v_add_f32_e32 v129, 0x4b400000, v129
	v_add_f32_e32 v130, 0x4b400000, v130
	v_add_f32_e32 v131, 0x4b400000, v131
	v_perm_b32 v124, v127, v124, s45
	v_perm_b32 v125, v126, v125, s46
	v_or_b32_e32 v176, v124, v125
	v_perm_b32 v128, v131, v128, s45
	v_perm_b32 v129, v130, v129, s46
	v_or_b32_e32 v177, v128, v129
	global_store_dwordx2 v1, v[176:177], s[42:43] offset:1536
	v_cvt_pk_bf16_f32 v254, v132, v133
	v_cvt_pk_bf16_f32 v255, v134, v135
	v_cvt_pk_bf16_f32 v94, v136, v137
	v_cvt_pk_bf16_f32 v95, v138, v139
	global_store_dwordx2 v241, v[254:255], s[38:39]
	global_store_dwordx2 v241, v[94:95], s[38:39] offset:8
	v_mul_f32_e32 v132, 0x41fe0000, v132
	v_mul_f32_e32 v133, 0x41fe0000, v133
; __device__ __forceinline__ unsigned pk2(float lo, float hi) { return cvt_pk_bf16(lo, hi); }
; __device__ __forceinline__ unsigned pk4_i8(float a, float b, float c, float d, float s) {
;     const unsigned ua = __float_as_uint(__builtin_amdgcn_fmed3f(a * s, -127.f, 127.f) + 12582912.f), ub = __float_as_uint(__builtin_amdgcn_fmed3f(b * s, -127.f, 127.f) + 12582912.f);
;     const unsigned uc = __float_as_uint(__builtin_amdgcn_fmed3f(c * s, -127.f, 127.f) + 12582912.f), ud = __float_as_uint(__builtin_amdgcn_fmed3f(d * s, -127.f, 127.f) + 12582912.f);
;     return (ua & 0xffu) | ((ub & 0xffu) << 8) | ((uc & 0xffu) << 16) | (ud << 24);
; template <bool WRITE_BF, bool WRITE_F32, bool WRITE_F8 = false>
; __device__ __forceinline__ void ln_phase(Frame& F, const bf16* T, const float* g, const float* b, unsigned char* x8 = nullptr) {
;     ...
;         for (int j = 0; j < 8; ++j) { const int c0 = 8 * (lane_ + 64 * j);
;             const f32x4 g0 = *(const f32x4*)(g + c0), g1 = *(const f32x4*)(g + c0 + 4), b0 = *(const f32x4*)(b + c0), b1 = *(const f32x4*)(b + c0 + 4);
;             const f32x4 y0 = (f32x4){v[8 * j], v[8 * j + 1], v[8 * j + 2], v[8 * j + 3]} * rstd * g0 + b0, y1 = (f32x4){v[8 * j + 4], v[8 * j + 5], v[8 * j + 6], v[8 * j + 7]} * rstd * g1 + b1;
;             if (WRITE_F32) { *(f32x4*)(Y + (size_t)row * D + c0) = y0; *(f32x4*)(Y + (size_t)row * D + c0 + 4) = y1; }
;             if (WRITE_BF) *(u32x4*)(xb + (size_t)row * D + c0) = (u32x4){pk2(y0[0], y0[1]), pk2(y0[2], y0[3]), pk2(y1[0], y1[1]), pk2(y1[2], y1[3])};
;             if (WRITE_F8) *(u32x2*)(x8 + (size_t)row * D + c0) = (u32x2){pk4_i8(y0[0], y0[1], y0[2], y0[3], I8_ACT), pk4_i8(y1[0], y1[1], y1[2], y1[3], I8_ACT)}; }
;     }
	v_mul_f32_e32 v134, 0x41fe0000, v134
	v_mul_f32_e32 v135, 0x41fe0000, v135
	v_mul_f32_e32 v136, 0x41fe0000, v136
	v_mul_f32_e32 v137, 0x41fe0000, v137
	v_mul_f32_e32 v138, 0x41fe0000, v138
	v_mul_f32_e32 v139, 0x41fe0000, v139
	v_med3_f32 v132, v132, s44, v203
	v_med3_f32 v133, v133, s44, v203
	v_med3_f32 v134, v134, s44, v203
	v_med3_f32 v135, v135, s44, v203
	v_med3_f32 v136, v136, s44, v203
	v_med3_f32 v137, v137, s44, v203
	v_med3_f32 v138, v138, s44, v203
	v_med3_f32 v139, v139, s44, v203
	v_add_f32_e32 v132, 0x4b400000, v132
	v_add_f32_e32 v133, 0x4b400000, v133
	v_add_f32_e32 v134, 0x4b400000, v134
	v_add_f32_e32 v135, 0x4b400000, v135
	v_add_f32_e32 v136, 0x4b400000, v136
	v_add_f32_e32 v137, 0x4b400000, v137
	v_add_f32_e32 v138, 0x4b400000, v138
	v_add_f32_e32 v139, 0x4b400000, v139
	v_perm_b32 v132, v135, v132, s45
	v_perm_b32 v133, v134, v133, s46
	v_or_b32_e32 v176, v132, v133
	v_perm_b32 v136, v139, v136, s45
	v_perm_b32 v137, v138, v137, s46
	v_or_b32_e32 v177, v136, v137
	global_store_dwordx2 v1, v[176:177], s[42:43] offset:2048
	v_cvt_pk_bf16_f32 v254, v140, v141
	v_cvt_pk_bf16_f32 v255, v142, v143
	v_cvt_pk_bf16_f32 v94, v144, v145
	v_cvt_pk_bf16_f32 v95, v146, v147
	global_store_dwordx2 v241, v[254:255], s[38:39] offset:1024
	global_store_dwordx2 v241, v[94:95], s[38:39] offset:1032
	v_mul_f32_e32 v140, 0x41fe0000, v140
	v_mul_f32_e32 v141, 0x41fe0000, v141
	v_mul_f32_e32 v142, 0x41fe0000, v142
	v_mul_f32_e32 v143, 0x41fe0000, v143
	v_mul_f32_e32 v144, 0x41fe0000, v144
	v_mul_f32_e32 v145, 0x41fe0000, v145
	v_mul_f32_e32 v146, 0x41fe0000, v146
	v_mul_f32_e32 v147, 0x41fe0000, v147
	v_med3_f32 v140, v140, s44, v203
	v_med3_f32 v141, v141, s44, v203
	v_med3_f32 v142, v142, s44, v203
	v_med3_f32 v143, v143, s44, v203
	v_med3_f32 v144, v144, s44, v203
	v_med3_f32 v145, v145, s44, v203
	v_med3_f32 v146, v146, s44, v203
	v_med3_f32 v147, v147, s44, v203
	v_add_f32_e32 v140, 0x4b400000, v140
	v_add_f32_e32 v141, 0x4b400000, v141
	v_add_f32_e32 v142, 0x4b400000, v142
	v_add_f32_e32 v143, 0x4b400000, v143
	v_add_f32_e32 v144, 0x4b400000, v144
	v_add_f32_e32 v145, 0x4b400000, v145
	v_add_f32_e32 v146, 0x4b400000, v146
	v_add_f32_e32 v147, 0x4b400000, v147
	v_perm_b32 v140, v143, v140, s45
	v_perm_b32 v141, v142, v141, s46
	v_or_b32_e32 v176, v140, v141
	v_perm_b32 v144, v147, v144, s45
	v_perm_b32 v145, v146, v145, s46
	v_or_b32_e32 v177, v144, v145
	global_store_dwordx2 v1, v[176:177], s[42:43] offset:2560
	v_cvt_pk_bf16_f32 v254, v148, v149
	v_cvt_pk_bf16_f32 v255, v150, v151
	v_cvt_pk_bf16_f32 v94, v152, v153
	v_cvt_pk_bf16_f32 v95, v154, v155
	global_store_dwordx2 v241, v[254:255], s[38:39] offset:2048
	global_store_dwordx2 v241, v[94:95], s[38:39] offset:2056
	v_mul_f32_e32 v148, 0x41fe0000, v148
	v_mul_f32_e32 v149, 0x41fe0000, v149
	v_mul_f32_e32 v150, 0x41fe0000, v150
	v_mul_f32_e32 v151, 0x41fe0000, v151
	v_mul_f32_e32 v152, 0x41fe0000, v152
	v_mul_f32_e32 v153, 0x41fe0000, v153
	v_mul_f32_e32 v154, 0x41fe0000, v154
	v_mul_f32_e32 v155, 0x41fe0000, v155
	v_med3_f32 v148, v148, s44, v203
	v_med3_f32 v149, v149, s44, v203
	v_med3_f32 v150, v150, s44, v203
	v_med3_f32 v151, v151, s44, v203
	v_med3_f32 v152, v152, s44, v203
	v_med3_f32 v153, v153, s44, v203
	v_med3_f32 v154, v154, s44, v203
	v_med3_f32 v155, v155, s44, v203
	v_add_f32_e32 v148, 0x4b400000, v148
	v_add_f32_e32 v149, 0x4b400000, v149
	v_add_f32_e32 v150, 0x4b400000, v150
	v_add_f32_e32 v151, 0x4b400000, v151
	v_add_f32_e32 v152, 0x4b400000, v152
	v_add_f32_e32 v153, 0x4b400000, v153
	v_add_f32_e32 v154, 0x4b400000, v154
	v_add_f32_e32 v155, 0x4b400000, v155
	v_perm_b32 v148, v151, v148, s45
	v_perm_b32 v149, v150, v149, s46
	v_or_b32_e32 v176, v148, v149
	v_perm_b32 v152, v155, v152, s45
	v_perm_b32 v153, v154, v153, s46
	v_or_b32_e32 v177, v152, v153
	global_store_dwordx2 v1, v[176:177], s[42:43] offset:3072
	v_cvt_pk_bf16_f32 v254, v204, v205
	v_cvt_pk_bf16_f32 v255, v206, v207
	v_cvt_pk_bf16_f32 v94, v208, v209
	v_cvt_pk_bf16_f32 v95, v210, v211
	global_store_dwordx2 v241, v[254:255], s[38:39] offset:3072
	global_store_dwordx2 v241, v[94:95], s[38:39] offset:3080
	v_mul_f32_e32 v204, 0x41fe0000, v204
	v_mul_f32_e32 v205, 0x41fe0000, v205
	v_mul_f32_e32 v206, 0x41fe0000, v206
	v_mul_f32_e32 v207, 0x41fe0000, v207
	v_mul_f32_e32 v208, 0x41fe0000, v208
	v_mul_f32_e32 v209, 0x41fe0000, v209
	v_mul_f32_e32 v210, 0x41fe0000, v210
	v_mul_f32_e32 v211, 0x41fe0000, v211
	v_med3_f32 v204, v204, s44, v203
	v_med3_f32 v205, v205, s44, v203
	v_med3_f32 v206, v206, s44, v203
	v_med3_f32 v207, v207, s44, v203
	v_med3_f32 v208, v208, s44, v203
	v_med3_f32 v209, v209, s44, v203
	v_med3_f32 v210, v210, s44, v203
	v_med3_f32 v211, v211, s44, v203
	v_add_f32_e32 v204, 0x4b400000, v204
	v_add_f32_e32 v205, 0x4b400000, v205
	v_add_f32_e32 v206, 0x4b400000, v206
	v_add_f32_e32 v207, 0x4b400000, v207
	v_add_f32_e32 v208, 0x4b400000, v208
	v_add_f32_e32 v209, 0x4b400000, v209
	v_add_f32_e32 v210, 0x4b400000, v210
	v_add_f32_e32 v211, 0x4b400000, v211
	v_perm_b32 v204, v207, v204, s45
	v_perm_b32 v205, v206, v205, s46
	v_or_b32_e32 v176, v204, v205
	v_perm_b32 v208, v211, v208, s45
	v_perm_b32 v209, v210, v209, s46
	v_or_b32_e32 v177, v208, v209
	global_store_dwordx2 v1, v[176:177], s[42:43] offset:3584
	s_add_i32 s41, s41, s92
	s_cmpk_lt_i32 s41, 0x4080
	s_cbranch_scc1 .Lln2_row
	s_branch .LBB0_1440

; template <bool WRITE_BF, bool WRITE_F32, bool WRITE_F8 = false>
; __device__ __forceinline__ void ln_phase(Frame& F, const bf16* T, const float* g, const float* b, unsigned char* x8 = nullptr) {
;     float* Y = F.out; bf16* xb = (bf16*)(F.ws + WS_XB);
;     int lane_ = threadIdx.x & 63; asm volatile("" : "+v"(lane_));
;     for (int row = F.gw; row < MR; row += F.NGW) {
;         const u32x4* tr = (const u32x4*)(T + (size_t)row * D) + lane_;
;         float v[64]; float s = 0.f;
; #pragma unroll
;         for (int j = 0; j < 8; ++j) { const u32x4 w = tr[64 * j];
; #pragma unroll
;             for (int q = 0; q < 4; ++q) { v[8 * j + 2 * q] = __uint_as_float(w[q] << 16); v[8 * j + 2 * q + 1] = __uint_as_float(w[q] & 0xffff0000u); s += v[8 * j + 2 * q] + v[8 * j + 2 * q + 1]; } }
.LBB0_1661:
	s_load_dwordx4 s[4:7], s[74:75], 0xe0
	s_load_dwordx4 s[52:55], s[74:75], 0x100
	v_mbcnt_lo_u32_b32 v203, -1, 0
	v_mbcnt_hi_u32_b32 v203, -1, v203
	v_lshlrev_b32_e32 v78, 4, v203
	v_add_u32_e32 v241, 0x1000, v78
	v_lshlrev_b32_e32 v1, 3, v203
	v_lshlrev_b32_e32 v92, 5, v203
	v_add_u32_e32 v24, 0x1000, v92
	v_add_u32_e32 v169, 0x2000, v92
	v_add_u32_e32 v179, 0x3000, v92
	s_waitcnt lgkmcnt(0)
	global_load_dwordx4 v[212:215], v92, s[4:5]
	global_load_dwordx4 v[216:219], v92, s[4:5] offset:16
	global_load_dwordx4 v[186:189], v92, s[6:7]
	global_load_dwordx4 v[190:193], v92, s[6:7] offset:16
	global_load_dwordx4 v[220:223], v92, s[4:5] offset:2048
	global_load_dwordx4 v[224:227], v92, s[4:5] offset:2064
	global_load_dwordx4 v[194:197], v92, s[6:7] offset:2048
	global_load_dwordx4 v[198:201], v92, s[6:7] offset:2064
	global_load_dwordx4 v[228:231], v24, s[4:5]
	global_load_dwordx4 v[232:235], v24, s[4:5] offset:16
	global_load_dwordx4 v[242:245], v24, s[6:7]
	global_load_dwordx4 v[246:249], v24, s[6:7] offset:16
	global_load_dwordx4 v[236:239], v24, s[4:5] offset:2048
	global_load_dwordx4 v[46:49], v24, s[4:5] offset:2064
	global_load_dwordx4 v[250:253], v24, s[6:7] offset:2048
	global_load_dwordx4 v[2:5], v24, s[6:7] offset:2064
	global_load_dwordx4 v[50:53], v169, s[4:5]
	global_load_dwordx4 v[54:57], v169, s[4:5] offset:16
	global_load_dwordx4 v[6:9], v169, s[6:7]
	global_load_dwordx4 v[10:13], v169, s[6:7] offset:16
	global_load_dwordx4 v[58:61], v169, s[4:5] offset:2048
	global_load_dwordx4 v[62:65], v169, s[4:5] offset:2064
	global_load_dwordx4 v[14:17], v169, s[6:7] offset:2048
	global_load_dwordx4 v[80:83], v169, s[6:7] offset:2064
	global_load_dwordx4 v[66:69], v179, s[4:5]
	global_load_dwordx4 v[70:73], v179, s[4:5] offset:16
	global_load_dwordx4 v[84:87], v179, s[6:7]
	global_load_dwordx4 v[88:91], v179, s[6:7] offset:16
	global_load_dwordx4 v[74:77], v179, s[4:5] offset:2048
	global_load_dwordx4 v[182:185], v179, s[4:5] offset:2064
	global_load_dwordx4 v[172:175], v179, s[6:7] offset:2048
	global_load_dwordx4 v[156:159], v179, s[6:7] offset:2064
	s_add_u32 s34, s54, 0x39900000
	s_addc_u32 s35, s55, 0
	s_mov_b32 s41, s94
.Lln3_row:
	s_lshl_b32 s36, s41, 13
	s_add_u32 s36, s34, s36
	s_addc_u32 s37, s35, 0
	global_load_dwordx4 v[104:107], v78, s[36:37]
	global_load_dwordx4 v[112:115], v78, s[36:37] offset:1024
	global_load_dwordx4 v[120:123], v78, s[36:37] offset:2048
	global_load_dwordx4 v[128:131], v78, s[36:37] offset:3072
	global_load_dwordx4 v[136:139], v241, s[36:37]
	global_load_dwordx4 v[144:147], v241, s[36:37] offset:1024
	global_load_dwordx4 v[152:155], v241, s[36:37] offset:2048
	global_load_dwordx4 v[208:211], v241, s[36:37] offset:3072
	v_mov_b32_e32 v160, 0
	v_mov_b32_e32 v161, 0
	s_waitcnt vmcnt(0)
	v_lshlrev_b32_e32 v100, 16, v104
	v_and_b32_e32 v101, 0xffff0000, v104
	v_lshlrev_b32_e32 v102, 16, v105
	v_and_b32_e32 v103, 0xffff0000, v105
	v_lshlrev_b32_e32 v104, 16, v106
	v_and_b32_e32 v105, 0xffff0000, v106
	v_lshlrev_b32_e32 v106, 16, v107
	v_and_b32_e32 v107, 0xffff0000, v107
	v_pk_add_f32 v[160:161], v[160:161], v[100:101]
	v_pk_add_f32 v[160:161], v[160:161], v[102:103]
	v_pk_add_f32 v[160:161], v[160:161], v[104:105]
	v_pk_add_f32 v[160:161], v[160:161], v[106:107]
	v_lshlrev_b32_e32 v108, 16, v112
	v_and_b32_e32 v109, 0xffff0000, v112
	v_lshlrev_b32_e32 v110, 16, v113
	v_and_b32_e32 v111, 0xffff0000, v113
	v_lshlrev_b32_e32 v112, 16, v114
	v_and_b32_e32 v113, 0xffff0000, v114
	v_lshlrev_b32_e32 v114, 16, v115
	v_and_b32_e32 v115, 0xffff0000, v115
	v_pk_add_f32 v[160:161], v[160:161], v[108:109]
	v_pk_add_f32 v[160:161], v[160:161], v[110:111]
	v_pk_add_f32 v[160:161], v[160:161], v[112:113]
	v_pk_add_f32 v[160:161], v[160:161], v[114:115]
	v_lshlrev_b32_e32 v116, 16, v120
	v_and_b32_e32 v117, 0xffff0000, v120
	v_lshlrev_b32_e32 v118, 16, v121
	v_and_b32_e32 v119, 0xffff0000, v121
	v_lshlrev_b32_e32 v120, 16, v122
	v_and_b32_e32 v121, 0xffff0000, v122
	v_lshlrev_b32_e32 v122, 16, v123
	v_and_b32_e32 v123, 0xffff0000, v123
	v_pk_add_f32 v[160:161], v[160:161], v[116:117]
	v_pk_add_f32 v[160:161], v[160:161], v[118:119]
	v_pk_add_f32 v[160:161], v[160:161], v[120:121]
	v_pk_add_f32 v[160:161], v[160:161], v[122:123]
	v_lshlrev_b32_e32 v124, 16, v128
	v_and_b32_e32 v125, 0xffff0000, v128
	v_lshlrev_b32_e32 v126, 16, v129
	v_and_b32_e32 v127, 0xffff0000, v129
	v_lshlrev_b32_e32 v128, 16, v130
	v_and_b32_e32 v129, 0xffff0000, v130
	v_lshlrev_b32_e32 v130, 16, v131
	v_and_b32_e32 v131, 0xffff0000, v131
	v_pk_add_f32 v[160:161], v[160:161], v[124:125]
	v_pk_add_f32 v[160:161], v[160:161], v[126:127]
	v_pk_add_f32 v[160:161], v[160:161], v[128:129]
	v_pk_add_f32 v[160:161], v[160:161], v[130:131]
	v_lshlrev_b32_e32 v132, 16, v136
	v_and_b32_e32 v133, 0xffff0000, v136
	v_lshlrev_b32_e32 v134, 16, v137
	v_and_b32_e32 v135, 0xffff0000, v137
	v_lshlrev_b32_e32 v136, 16, v138
	v_and_b32_e32 v137, 0xffff0000, v138
	v_lshlrev_b32_e32 v138, 16, v139
	v_and_b32_e32 v139, 0xffff0000, v139
	v_pk_add_f32 v[160:161], v[160:161], v[132:133]
	v_pk_add_f32 v[160:161], v[160:161], v[134:135]
	v_pk_add_f32 v[160:161], v[160:161], v[136:137]
	v_pk_add_f32 v[160:161], v[160:161], v[138:139]
	v_lshlrev_b32_e32 v140, 16, v144
	v_and_b32_e32 v141, 0xffff0000, v144
	v_lshlrev_b32_e32 v142, 16, v145
	v_and_b32_e32 v143, 0xffff0000, v145
	v_lshlrev_b32_e32 v144, 16, v146
	v_and_b32_e32 v145, 0xffff0000, v146
	v_lshlrev_b32_e32 v146, 16, v147
	v_and_b32_e32 v147, 0xffff0000, v147
	v_pk_add_f32 v[160:161], v[160:161], v[140:141]
	v_pk_add_f32 v[160:161], v[160:161], v[142:143]
	v_pk_add_f32 v[160:161], v[160:161], v[144:145]
; template <bool WRITE_BF, bool WRITE_F32, bool WRITE_F8 = false>
; __device__ __forceinline__ void ln_phase(Frame& F, const bf16* T, const float* g, const float* b, unsigned char* x8 = nullptr) {
;     ...
;             for (int q = 0; q < 4; ++q) { v[8 * j + 2 * q] = __uint_as_float(w[q] << 16); v[8 * j + 2 * q + 1] = __uint_as_float(w[q] & 0xffff0000u); s += v[8 * j + 2 * q] + v[8 * j + 2 * q + 1]; } }
;         const float mean = wave_sum(s) * (1.f / D); float s2 = 0.f;
; #pragma unroll
;         for (int i = 0; i < 64; ++i) { v[i] -= mean; s2 += v[i] * v[i]; }
	v_pk_add_f32 v[160:161], v[160:161], v[146:147]
	v_lshlrev_b32_e32 v148, 16, v152
	v_and_b32_e32 v149, 0xffff0000, v152
	v_lshlrev_b32_e32 v150, 16, v153
	v_and_b32_e32 v151, 0xffff0000, v153
	v_lshlrev_b32_e32 v152, 16, v154
	v_and_b32_e32 v153, 0xffff0000, v154
	v_lshlrev_b32_e32 v154, 16, v155
	v_and_b32_e32 v155, 0xffff0000, v155
	v_pk_add_f32 v[160:161], v[160:161], v[148:149]
	v_pk_add_f32 v[160:161], v[160:161], v[150:151]
	v_pk_add_f32 v[160:161], v[160:161], v[152:153]
	v_pk_add_f32 v[160:161], v[160:161], v[154:155]
	v_lshlrev_b32_e32 v204, 16, v208
	v_and_b32_e32 v205, 0xffff0000, v208
	v_lshlrev_b32_e32 v206, 16, v209
	v_and_b32_e32 v207, 0xffff0000, v209
	v_lshlrev_b32_e32 v208, 16, v210
	v_and_b32_e32 v209, 0xffff0000, v210
	v_lshlrev_b32_e32 v210, 16, v211
	v_and_b32_e32 v211, 0xffff0000, v211
	v_pk_add_f32 v[160:161], v[160:161], v[204:205]
	v_pk_add_f32 v[160:161], v[160:161], v[206:207]
	v_pk_add_f32 v[160:161], v[160:161], v[208:209]
	v_pk_add_f32 v[160:161], v[160:161], v[210:211]
	v_add_f32_e32 v99, v160, v161
	s_nop 1
	v_add_f32_dpp v99, v99, v99 quad_perm:[1,0,3,2] row_mask:0xf bank_mask:0xf
	s_nop 1
	v_add_f32_dpp v99, v99, v99 quad_perm:[2,3,0,1] row_mask:0xf bank_mask:0xf
	s_nop 1
	v_add_f32_dpp v99, v99, v99 row_half_mirror row_mask:0xf bank_mask:0xf
	s_nop 1
	v_add_f32_dpp v99, v99, v99 row_mirror row_mask:0xf bank_mask:0xf
	s_nop 1
	v_readlane_b32 s28, v99, 0
	v_readlane_b32 s29, v99, 16
	v_readlane_b32 s30, v99, 32
	v_readlane_b32 s31, v99, 48
	s_nop 1
	v_mov_b32_e32 v99, s28
	v_add_f32_e32 v99, s29, v99
	v_add_f32_e32 v203, s30, v99
	v_add_f32_e32 v99, s31, v203
	v_mul_f32_e32 v18, 0xb9800000, v99
	v_mov_b32_e32 v160, 0
	v_mov_b32_e32 v161, 0
	v_pk_add_f32 v[100:101], v[100:101], v[18:19] op_sel_hi:[1,0]
	v_pk_add_f32 v[102:103], v[102:103], v[18:19] op_sel_hi:[1,0]
	v_pk_add_f32 v[104:105], v[104:105], v[18:19] op_sel_hi:[1,0]
	v_pk_add_f32 v[106:107], v[106:107], v[18:19] op_sel_hi:[1,0]
	v_pk_add_f32 v[108:109], v[108:109], v[18:19] op_sel_hi:[1,0]
	v_pk_add_f32 v[110:111], v[110:111], v[18:19] op_sel_hi:[1,0]
	v_pk_add_f32 v[112:113], v[112:113], v[18:19] op_sel_hi:[1,0]
	v_pk_add_f32 v[114:115], v[114:115], v[18:19] op_sel_hi:[1,0]
	v_pk_add_f32 v[116:117], v[116:117], v[18:19] op_sel_hi:[1,0]
	v_pk_add_f32 v[118:119], v[118:119], v[18:19] op_sel_hi:[1,0]
	v_pk_add_f32 v[120:121], v[120:121], v[18:19] op_sel_hi:[1,0]
	v_pk_add_f32 v[122:123], v[122:123], v[18:19] op_sel_hi:[1,0]
	v_pk_add_f32 v[124:125], v[124:125], v[18:19] op_sel_hi:[1,0]
	v_pk_add_f32 v[126:127], v[126:127], v[18:19] op_sel_hi:[1,0]
	v_pk_add_f32 v[128:129], v[128:129], v[18:19] op_sel_hi:[1,0]
	v_pk_add_f32 v[130:131], v[130:131], v[18:19] op_sel_hi:[1,0]
	v_pk_add_f32 v[132:133], v[132:133], v[18:19] op_sel_hi:[1,0]
	v_pk_add_f32 v[134:135], v[134:135], v[18:19] op_sel_hi:[1,0]
	v_pk_add_f32 v[136:137], v[136:137], v[18:19] op_sel_hi:[1,0]
	v_pk_add_f32 v[138:139], v[138:139], v[18:19] op_sel_hi:[1,0]
	v_pk_add_f32 v[140:141], v[140:141], v[18:19] op_sel_hi:[1,0]
	v_pk_add_f32 v[142:143], v[142:143], v[18:19] op_sel_hi:[1,0]
	v_pk_add_f32 v[144:145], v[144:145], v[18:19] op_sel_hi:[1,0]
	v_pk_add_f32 v[146:147], v[146:147], v[18:19] op_sel_hi:[1,0]
	v_pk_add_f32 v[148:149], v[148:149], v[18:19] op_sel_hi:[1,0]
	v_pk_add_f32 v[150:151], v[150:151], v[18:19] op_sel_hi:[1,0]
	v_pk_add_f32 v[152:153], v[152:153], v[18:19] op_sel_hi:[1,0]
	v_pk_add_f32 v[154:155], v[154:155], v[18:19] op_sel_hi:[1,0]
	v_pk_add_f32 v[204:205], v[204:205], v[18:19] op_sel_hi:[1,0]
	v_pk_add_f32 v[206:207], v[206:207], v[18:19] op_sel_hi:[1,0]
	v_pk_add_f32 v[208:209], v[208:209], v[18:19] op_sel_hi:[1,0]
	v_pk_add_f32 v[210:211], v[210:211], v[18:19] op_sel_hi:[1,0]
	v_pk_fma_f32 v[160:161], v[100:101], v[100:101], v[160:161]
	v_pk_fma_f32 v[160:161], v[102:103], v[102:103], v[160:161]
	v_pk_fma_f32 v[160:161], v[104:105], v[104:105], v[160:161]
	v_pk_fma_f32 v[160:161], v[106:107], v[106:107], v[160:161]
	v_pk_fma_f32 v[160:161], v[108:109], v[108:109], v[160:161]
	v_pk_fma_f32 v[160:161], v[110:111], v[110:111], v[160:161]
	v_pk_fma_f32 v[160:161], v[112:113], v[112:113], v[160:161]
	v_pk_fma_f32 v[160:161], v[114:115], v[114:115], v[160:161]
	v_pk_fma_f32 v[160:161], v[116:117], v[116:117], v[160:161]
	v_pk_fma_f32 v[160:161], v[118:119], v[118:119], v[160:161]
	v_pk_fma_f32 v[160:161], v[120:121], v[120:121], v[160:161]
	v_pk_fma_f32 v[160:161], v[122:123], v[122:123], v[160:161]
	v_pk_fma_f32 v[160:161], v[124:125], v[124:125], v[160:161]
	v_pk_fma_f32 v[160:161], v[126:127], v[126:127], v[160:161]
	v_pk_fma_f32 v[160:161], v[128:129], v[128:129], v[160:161]
	v_pk_fma_f32 v[160:161], v[130:131], v[130:131], v[160:161]
	v_pk_fma_f32 v[160:161], v[132:133], v[132:133], v[160:161]
	v_pk_fma_f32 v[160:161], v[134:135], v[134:135], v[160:161]
	v_pk_fma_f32 v[160:161], v[136:137], v[136:137], v[160:161]
	v_pk_fma_f32 v[160:161], v[138:139], v[138:139], v[160:161]
	v_pk_fma_f32 v[160:161], v[140:141], v[140:141], v[160:161]
	v_pk_fma_f32 v[160:161], v[142:143], v[142:143], v[160:161]
	v_pk_fma_f32 v[160:161], v[144:145], v[144:145], v[160:161]
	v_pk_fma_f32 v[160:161], v[146:147], v[146:147], v[160:161]
	v_pk_fma_f32 v[160:161], v[148:149], v[148:149], v[160:161]
	v_pk_fma_f32 v[160:161], v[150:151], v[150:151], v[160:161]
	v_pk_fma_f32 v[160:161], v[152:153], v[152:153], v[160:161]
	v_pk_fma_f32 v[160:161], v[154:155], v[154:155], v[160:161]
	v_pk_fma_f32 v[160:161], v[204:205], v[204:205], v[160:161]
	v_pk_fma_f32 v[160:161], v[206:207], v[206:207], v[160:161]
	v_pk_fma_f32 v[160:161], v[208:209], v[208:209], v[160:161]
; __device__ __forceinline__ unsigned pk2(float lo, float hi) { return cvt_pk_bf16(lo, hi); }
; template <bool WRITE_BF, bool WRITE_F32, bool WRITE_F8 = false>
; __device__ __forceinline__ void ln_phase(Frame& F, const bf16* T, const float* g, const float* b, unsigned char* x8 = nullptr) {
;     ...
;         for (int i = 0; i < 64; ++i) { v[i] -= mean; s2 += v[i] * v[i]; }
;         const float rstd = 1.f / sqrtf(wave_sum(s2) * (1.f / D) + 1e-5f);
; #pragma unroll
;         for (int j = 0; j < 8; ++j) { const int c0 = 8 * (lane_ + 64 * j);
;             const f32x4 g0 = *(const f32x4*)(g + c0), g1 = *(const f32x4*)(g + c0 + 4), b0 = *(const f32x4*)(b + c0), b1 = *(const f32x4*)(b + c0 + 4);
;             const f32x4 y0 = (f32x4){v[8 * j], v[8 * j + 1], v[8 * j + 2], v[8 * j + 3]} * rstd * g0 + b0, y1 = (f32x4){v[8 * j + 4], v[8 * j + 5], v[8 * j + 6], v[8 * j + 7]} * rstd * g1 + b1;
;             if (WRITE_F32) { *(f32x4*)(Y + (size_t)row * D + c0) = y0; *(f32x4*)(Y + (size_t)row * D + c0 + 4) = y1; }
;             if (WRITE_BF) *(u32x4*)(xb + (size_t)row * D + c0) = (u32x4){pk2(y0[0], y0[1]), pk2(y0[2], y0[3]), pk2(y1[0], y1[1]), pk2(y1[2], y1[3])};
;             if (WRITE_F8) *(u32x2*)(x8 + (size_t)row * D + c0) = (u32x2){pk4_i8(y0[0], y0[1], y0[2], y0[3], I8_ACT), pk4_i8(y1[0], y1[1], y1[2], y1[3], I8_ACT)}; }
;     }
	v_pk_fma_f32 v[160:161], v[210:211], v[210:211], v[160:161]
	v_add_f32_e32 v99, v160, v161
	s_nop 1
	v_add_f32_dpp v99, v99, v99 quad_perm:[1,0,3,2] row_mask:0xf bank_mask:0xf
	s_nop 1
	v_add_f32_dpp v99, v99, v99 quad_perm:[2,3,0,1] row_mask:0xf bank_mask:0xf
	s_nop 1
	v_add_f32_dpp v99, v99, v99 row_half_mirror row_mask:0xf bank_mask:0xf
	s_nop 1
	v_add_f32_dpp v99, v99, v99 row_mirror row_mask:0xf bank_mask:0xf
	s_nop 1
	v_readlane_b32 s28, v99, 0
	v_readlane_b32 s29, v99, 16
	v_readlane_b32 s30, v99, 32
	v_readlane_b32 s31, v99, 48
	s_nop 1
	v_mov_b32_e32 v99, s28
	v_add_f32_e32 v99, s29, v99
	v_add_f32_e32 v203, s30, v99
	v_add_f32_e32 v99, s31, v203
	v_mov_b32_e32 v203, 0x3727c5ac
	v_fmac_f32_e32 v203, 0x39800000, v99
	v_sqrt_f32_e32 v203, v203
	s_nop 0
	v_rcp_f32_e32 v18, v203
	s_nop 0
	v_pk_mul_f32 v[100:101], v[100:101], v[18:19] op_sel_hi:[1,0]
	v_pk_mul_f32 v[102:103], v[102:103], v[18:19] op_sel_hi:[1,0]
	v_pk_mul_f32 v[104:105], v[104:105], v[18:19] op_sel_hi:[1,0]
	v_pk_mul_f32 v[106:107], v[106:107], v[18:19] op_sel_hi:[1,0]
	v_pk_mul_f32 v[108:109], v[108:109], v[18:19] op_sel_hi:[1,0]
	v_pk_mul_f32 v[110:111], v[110:111], v[18:19] op_sel_hi:[1,0]
	v_pk_mul_f32 v[112:113], v[112:113], v[18:19] op_sel_hi:[1,0]
	v_pk_mul_f32 v[114:115], v[114:115], v[18:19] op_sel_hi:[1,0]
	v_pk_mul_f32 v[116:117], v[116:117], v[18:19] op_sel_hi:[1,0]
	v_pk_mul_f32 v[118:119], v[118:119], v[18:19] op_sel_hi:[1,0]
	v_pk_mul_f32 v[120:121], v[120:121], v[18:19] op_sel_hi:[1,0]
	v_pk_mul_f32 v[122:123], v[122:123], v[18:19] op_sel_hi:[1,0]
	v_pk_mul_f32 v[124:125], v[124:125], v[18:19] op_sel_hi:[1,0]
	v_pk_mul_f32 v[126:127], v[126:127], v[18:19] op_sel_hi:[1,0]
	v_pk_mul_f32 v[128:129], v[128:129], v[18:19] op_sel_hi:[1,0]
	v_pk_mul_f32 v[130:131], v[130:131], v[18:19] op_sel_hi:[1,0]
	v_pk_mul_f32 v[132:133], v[132:133], v[18:19] op_sel_hi:[1,0]
	v_pk_mul_f32 v[134:135], v[134:135], v[18:19] op_sel_hi:[1,0]
	v_pk_mul_f32 v[136:137], v[136:137], v[18:19] op_sel_hi:[1,0]
	v_pk_mul_f32 v[138:139], v[138:139], v[18:19] op_sel_hi:[1,0]
	v_pk_mul_f32 v[140:141], v[140:141], v[18:19] op_sel_hi:[1,0]
	v_pk_mul_f32 v[142:143], v[142:143], v[18:19] op_sel_hi:[1,0]
	v_pk_mul_f32 v[144:145], v[144:145], v[18:19] op_sel_hi:[1,0]
	v_pk_mul_f32 v[146:147], v[146:147], v[18:19] op_sel_hi:[1,0]
	v_pk_mul_f32 v[148:149], v[148:149], v[18:19] op_sel_hi:[1,0]
	v_pk_mul_f32 v[150:151], v[150:151], v[18:19] op_sel_hi:[1,0]
	v_pk_mul_f32 v[152:153], v[152:153], v[18:19] op_sel_hi:[1,0]
	v_pk_mul_f32 v[154:155], v[154:155], v[18:19] op_sel_hi:[1,0]
	v_pk_mul_f32 v[204:205], v[204:205], v[18:19] op_sel_hi:[1,0]
	v_pk_mul_f32 v[206:207], v[206:207], v[18:19] op_sel_hi:[1,0]
	v_pk_mul_f32 v[208:209], v[208:209], v[18:19] op_sel_hi:[1,0]
	v_pk_mul_f32 v[210:211], v[210:211], v[18:19] op_sel_hi:[1,0]
	v_pk_fma_f32 v[100:101], v[212:213], v[100:101], v[186:187]
	v_pk_fma_f32 v[102:103], v[214:215], v[102:103], v[188:189]
	v_pk_fma_f32 v[104:105], v[216:217], v[104:105], v[190:191]
	v_pk_fma_f32 v[106:107], v[218:219], v[106:107], v[192:193]
	v_pk_fma_f32 v[108:109], v[220:221], v[108:109], v[194:195]
	v_pk_fma_f32 v[110:111], v[222:223], v[110:111], v[196:197]
	v_pk_fma_f32 v[112:113], v[224:225], v[112:113], v[198:199]
	v_pk_fma_f32 v[114:115], v[226:227], v[114:115], v[200:201]
	v_pk_fma_f32 v[116:117], v[228:229], v[116:117], v[242:243]
	v_pk_fma_f32 v[118:119], v[230:231], v[118:119], v[244:245]
	v_pk_fma_f32 v[120:121], v[232:233], v[120:121], v[246:247]
	v_pk_fma_f32 v[122:123], v[234:235], v[122:123], v[248:249]
	v_pk_fma_f32 v[124:125], v[236:237], v[124:125], v[250:251]
	v_pk_fma_f32 v[126:127], v[238:239], v[126:127], v[252:253]
	v_pk_fma_f32 v[128:129], v[46:47], v[128:129], v[2:3]
	v_pk_fma_f32 v[130:131], v[48:49], v[130:131], v[4:5]
	v_pk_fma_f32 v[132:133], v[50:51], v[132:133], v[6:7]
	v_pk_fma_f32 v[134:135], v[52:53], v[134:135], v[8:9]
	v_pk_fma_f32 v[136:137], v[54:55], v[136:137], v[10:11]
	v_pk_fma_f32 v[138:139], v[56:57], v[138:139], v[12:13]
	v_pk_fma_f32 v[140:141], v[58:59], v[140:141], v[14:15]
	v_pk_fma_f32 v[142:143], v[60:61], v[142:143], v[16:17]
	v_pk_fma_f32 v[144:145], v[62:63], v[144:145], v[80:81]
	v_pk_fma_f32 v[146:147], v[64:65], v[146:147], v[82:83]
	v_pk_fma_f32 v[148:149], v[66:67], v[148:149], v[84:85]
	v_pk_fma_f32 v[150:151], v[68:69], v[150:151], v[86:87]
	v_pk_fma_f32 v[152:153], v[70:71], v[152:153], v[88:89]
	v_pk_fma_f32 v[154:155], v[72:73], v[154:155], v[90:91]
	v_pk_fma_f32 v[204:205], v[74:75], v[204:205], v[172:173]
	v_pk_fma_f32 v[206:207], v[76:77], v[206:207], v[174:175]
	v_pk_fma_f32 v[208:209], v[182:183], v[208:209], v[156:157]
	v_pk_fma_f32 v[210:211], v[184:185], v[210:211], v[158:159]
	s_lshl_b32 s38, s41, 14
	s_add_u32 s38, s52, s38
	s_addc_u32 s39, s53, 0
	global_store_dwordx4 v92, v[100:103], s[38:39]
	global_store_dwordx4 v92, v[104:107], s[38:39] offset:16
	global_store_dwordx4 v92, v[108:111], s[38:39] offset:2048
	global_store_dwordx4 v92, v[112:115], s[38:39] offset:2064
	global_store_dwordx4 v24, v[116:119], s[38:39]
	global_store_dwordx4 v24, v[120:123], s[38:39] offset:16
	global_store_dwordx4 v24, v[124:127], s[38:39] offset:2048
	global_store_dwordx4 v24, v[128:131], s[38:39] offset:2064
	global_store_dwordx4 v169, v[132:135], s[38:39]
	global_store_dwordx4 v169, v[136:139], s[38:39] offset:16
	global_store_dwordx4 v169, v[140:143], s[38:39] offset:2048
	global_store_dwordx4 v169, v[144:147], s[38:39] offset:2064
	global_store_dwordx4 v179, v[148:151], s[38:39]
	global_store_dwordx4 v179, v[152:155], s[38:39] offset:16
	global_store_dwordx4 v179, v[204:207], s[38:39] offset:2048
	global_store_dwordx4 v179, v[208:211], s[38:39] offset:2064
	s_add_i32 s41, s41, s92
	s_cmpk_lt_i32 s41, 0x4080
	s_cbranch_scc1 .Lln3_row
	s_branch .LBB0_1662
